# speedup vs baseline: 1.0129x; 1.0129x over previous
; #define WAIT_V(n) asm volatile("s_waitcnt vmcnt(%0)" ::"n"(n) : "memory")
; #define BAR __builtin_amdgcn_s_barrier()
; template <int EPI, bool SWP> ...
;     ...
;   } else {
;     if (wr == 1) BAR;
;     WAIT_V(0); BAR;
;     BAR;
;   }
;   float ss_next = 0.f;
;   if (has_next && e.nss > 0 && tid < 256)
;     for (int i = 0; i < e.nss; ++i) ss_next += e.ss[(size_t)(brow_n + tid) * e.nss + i];
.LBB0_96:
	s_waitcnt vmcnt(8)
	s_barrier
	s_barrier
	s_nor_b64 s[84:85], s[4:5], s[58:59]
	v_mov_b32_e32 v235, 0x358637bd
	s_and_saveexec_b64 s[76:77], s[84:85]
	s_cbranch_execnz .LBB0_79
	s_branch .LBB0_80

; #define WAIT_V(n) asm volatile("s_waitcnt vmcnt(%0)" ::"n"(n) : "memory")
; #define BAR __builtin_amdgcn_s_barrier()
; template <int EPI, bool SWP> ...
;     ...
;   } else {
;     if (wr == 1) BAR;
;     WAIT_V(0); BAR;
;     BAR;
.LBB0_121:
	s_waitcnt vmcnt(8)
	s_barrier
	s_barrier

; #define SCHED() __builtin_amdgcn_sched_barrier(0)
; template <int EPI, int MB, int NB> ...
;     ...
;   } else if constexpr (EPI == EPI_RES) {
;     const float* res = brow < e.res_split ? e.res0 + (size_t)brow * DM : e.res1 + (size_t)(brow - e.res_split) * DM;
;     const bool rb = e.resb != nullptr;
; #pragma unroll
;     for (int m = 0; m < MB; ++m) {
;       const int lr = lrow0 + m * 16;
;       float sq = 0.f;
;       u32x2 ob[2], rw[2];
;       if (rb) unwiden16(*(const i32x4*)(e.resb + (size_t)(brow + lr) * DM + colw), rw[0], rw[1]);
; #pragma unroll
;       for (int n = 0; n < NB; ++n) {
;         const int col = col0 + n * 16;
;         float4 r4;
;         if (rb) {
;           const u32x2 rr = rw[n];
;           r4.x = __uint_as_float(rr[0] << 16); r4.y = __uint_as_float(rr[0] & 0xffff0000u);
;           r4.z = __uint_as_float(rr[1] << 16); r4.w = __uint_as_float(rr[1] & 0xffff0000u);
;         } else {
;           r4 = *(const float4*)(res + (size_t)lr * DM + col);
;         }
;         float4 v;
;         v.x = r4.x + e.alpha * acc[m][n][0]; v.y = r4.y + e.alpha * acc[m][n][1];
;         v.z = r4.z + e.alpha * acc[m][n][2]; v.w = r4.w + e.alpha * acc[m][n][3];
;         ob[n][0] = pk_bf16(v.x, v.y); ob[n][1] = pk_bf16(v.z, v.w);
;         sq += v.x * v.x + v.y * v.y + v.z * v.z + v.w * v.w;
;       }
;       *(i32x4*)(e.o16 + (size_t)(brow + lr) * DM + colw) = widen16(ob[0], ob[1]);
;       sq += __shfl_xor(sq, 16); sq += __shfl_xor(sq, 32);
;       if (fq == 0) s_part[part_slot * 256 + lr] = sq;
;       SCHED();
;     }
.LBB0_130:
	v_readlane_b32 s68, v254, 6
	v_and_b32_e32 v133, 64, v218
	s_add_i32 s10, s1, 0xffff8000
	v_readlane_b32 s69, v254, 7
	v_xor_b32_e32 v131, 16, v218
	v_add_u32_e32 v133, 64, v133
	s_cmpk_lt_i32 s66, 0x80
	v_readlane_b32 s70, v254, 8
	v_readlane_b32 s71, v254, 9
	s_mov_b64 s[52:53], s[68:69]
	v_cmp_lt_i32_e32 vcc, v131, v133
	s_cselect_b32 s11, s67, 0
	s_cselect_b32 s10, s1, s10
	s_mov_b64 s[54:55], s[70:71]
	v_cndmask_b32_e32 v131, v218, v131, vcc
	v_mov_b32_e32 v132, v209
	v_mov_b32_e32 v128, v210
	s_cselect_b32 s48, s53, s55
	s_cselect_b32 s49, s52, s54
	s_lshl_b64 s[10:11], s[10:11], 13
	v_lshlrev_b32_e32 v135, 2, v131
	v_xor_b32_e32 v131, 32, v218
	s_add_u32 s10, s49, s10
	v_cmp_lt_i32_e32 vcc, v131, v133
	v_ashrrev_i32_e32 v133, 31, v132
	v_add_u32_e32 v130, s65, v128
	s_addc_u32 s11, s48, s11
	v_cndmask_b32_e32 v131, v218, v131, vcc
	v_lshlrev_b64 v[136:137], 13, v[132:133]
	v_lshlrev_b32_e32 v134, 2, v131
	v_lshl_add_u64 v[136:137], s[10:11], 0, v[136:137]
	v_ashrrev_i32_e32 v131, 31, v130
	v_lshl_add_u64 v[140:141], v[130:131], 2, v[136:137]
	v_mov_b32_e32 v252, 0x20000
	v_mov_b32_e32 v253, 0
	global_load_dwordx4 v[232:235], v[140:141], off
	global_load_dwordx4 v[236:239], v[140:141], off offset:64
	v_lshl_add_u64 v[248:249], v[140:141], 0, v[252:253]
	global_load_dwordx4 v[240:243], v[248:249], off
	global_load_dwordx4 v[244:247], v[248:249], off offset:64
	v_readlane_b32 s52, v254, 38
	v_add_u32_e32 v128, v130, v211
	v_readlane_b32 s54, v254, 40
	v_readlane_b32 s55, v254, 41
	v_ashrrev_i32_e32 v129, 31, v128
	v_readlane_b32 s53, v254, 39
	v_readlane_b32 s72, v254, 10
	v_readlane_b32 s73, v254, 11
	v_readlane_b32 s74, v254, 12
	v_readlane_b32 s75, v254, 13
	v_readlane_b32 s76, v254, 14
	v_readlane_b32 s77, v254, 15
	v_readlane_b32 s78, v254, 16
	v_readlane_b32 s79, v254, 17
	v_readlane_b32 s80, v254, 18
	v_readlane_b32 s81, v254, 19
	v_readlane_b32 s82, v254, 20
	v_readlane_b32 s83, v254, 21
	s_waitcnt vmcnt(3)
	v_mov_b32_e32 v136, v232
	v_mov_b32_e32 v137, v233
	v_mov_b32_e32 v138, v234
	v_mov_b32_e32 v139, v235
	v_pk_fma_f32 v[136:137], v[124:125], 0.5, v[136:137] op_sel_hi:[1,0,1]
	v_pk_fma_f32 v[126:127], v[126:127], 0.5, v[138:139] op_sel_hi:[1,0,1]
	v_cvt_pk_bf16_f32 v124, v136, v137
	v_pk_mul_f32 v[142:143], v[136:137], v[136:137]
	v_cvt_pk_bf16_f32 v125, v126, v127
	v_pk_mul_f32 v[144:145], v[126:127], v[126:127]
	s_waitcnt vmcnt(2)
	v_mov_b32_e32 v136, v236
	v_mov_b32_e32 v137, v237
	v_mov_b32_e32 v138, v238
	v_mov_b32_e32 v139, v239
	v_pk_fma_f32 v[120:121], v[120:121], 0.5, v[136:137] op_sel_hi:[1,0,1]
	v_pk_fma_f32 v[122:123], v[122:123], 0.5, v[138:139] op_sel_hi:[1,0,1]
	v_cvt_pk_bf16_f32 v126, v120, v121
	v_pk_mul_f32 v[120:121], v[120:121], v[120:121]
	v_cvt_pk_bf16_f32 v127, v122, v123
	v_pk_mul_f32 v[122:123], v[122:123], v[122:123]
	v_add_f32_e32 v120, v120, v121
	v_add_f32_e32 v121, v142, v143
	v_add_f32_e32 v120, v122, v120
	v_add_f32_e32 v121, v144, v121
	v_add_f32_e32 v120, v123, v120
	v_add_f32_e32 v121, v145, v121
	v_add_f32_e32 v122, v121, v120
	v_add_u32_e32 v120, s1, v132
	v_ashrrev_i32_e32 v121, 31, v120
	v_lshlrev_b64 v[120:121], 12, v[120:121]
	v_lshl_add_u64 v[120:121], s[54:55], 0, v[120:121]
	v_permlane16_swap_b32_e32 v124, v126
	v_permlane16_swap_b32_e32 v125, v127
	v_lshl_add_u64 v[120:121], v[128:129], 1, v[120:121]
	global_store_dwordx4 v[120:121], v[124:127], off
	ds_bpermute_b32 v120, v135, v122
	s_waitcnt lgkmcnt(0)
	v_add_f32_e32 v121, v122, v120
	ds_bpermute_b32 v122, v134, v121
	v_lshl_add_u32 v120, v132, 2, s16
	s_and_saveexec_b64 s[48:49], s[8:9]
	s_cbranch_execz .LBB0_132
	s_waitcnt lgkmcnt(0)
	v_add_f32_e32 v121, v121, v122
	ds_write_b32 v120, v121
.LBB0_132:
	s_or_b64 exec, exec, s[48:49]
	v_add_u32_e32 v126, 16, v132
	v_ashrrev_i32_e32 v127, 31, v126
	s_waitcnt lgkmcnt(0)
	v_lshlrev_b64 v[122:123], 13, v[126:127]
	v_lshl_add_u64 v[122:123], s[10:11], 0, v[122:123]
	v_lshl_add_u64 v[136:137], v[130:131], 2, v[122:123]
	s_waitcnt vmcnt(2)
	v_mov_b32_e32 v122, v240
	v_mov_b32_e32 v123, v241
	v_mov_b32_e32 v124, v242
	v_mov_b32_e32 v125, v243
	v_pk_fma_f32 v[122:123], v[116:117], 0.5, v[122:123] op_sel_hi:[1,0,1]
	v_pk_fma_f32 v[118:119], v[118:119], 0.5, v[124:125] op_sel_hi:[1,0,1]
	v_cvt_pk_bf16_f32 v116, v122, v123
	v_pk_mul_f32 v[138:139], v[122:123], v[122:123]
	v_cvt_pk_bf16_f32 v117, v118, v119
	v_pk_mul_f32 v[140:141], v[118:119], v[118:119]
	s_waitcnt vmcnt(1)
	v_mov_b32_e32 v122, v244
	v_mov_b32_e32 v123, v245
	v_mov_b32_e32 v124, v246
	v_mov_b32_e32 v125, v247
	v_pk_fma_f32 v[112:113], v[112:113], 0.5, v[122:123] op_sel_hi:[1,0,1]
	v_pk_fma_f32 v[114:115], v[114:115], 0.5, v[124:125] op_sel_hi:[1,0,1]
	v_cvt_pk_bf16_f32 v118, v112, v113
	v_pk_mul_f32 v[112:113], v[112:113], v[112:113]
	v_cvt_pk_bf16_f32 v119, v114, v115
	v_pk_mul_f32 v[114:115], v[114:115], v[114:115]
	v_add_f32_e32 v112, v112, v113
	v_add_f32_e32 v113, v138, v139
	v_add_f32_e32 v112, v114, v112
	v_add_f32_e32 v113, v140, v113
	v_add_f32_e32 v112, v115, v112
	v_add_f32_e32 v113, v141, v113
	v_add_f32_e32 v114, v113, v112
	v_add_u32_e32 v112, s1, v126
	v_ashrrev_i32_e32 v113, 31, v112
	v_lshlrev_b64 v[112:113], 12, v[112:113]
	v_lshl_add_u64 v[112:113], s[54:55], 0, v[112:113]
	v_permlane16_swap_b32_e32 v116, v118
	v_permlane16_swap_b32_e32 v117, v119
	v_lshl_add_u64 v[112:113], v[128:129], 1, v[112:113]
	global_store_dwordx4 v[112:113], v[116:119], off
	ds_bpermute_b32 v112, v135, v114
	s_waitcnt lgkmcnt(0)
	v_add_f32_e32 v112, v114, v112
	ds_bpermute_b32 v113, v134, v112
	s_and_saveexec_b64 s[48:49], s[8:9]
	s_cbranch_execz .LBB0_134
	s_waitcnt lgkmcnt(0)
	v_add_f32_e32 v112, v112, v113
	ds_write_b32 v120, v112 offset:64
; #define SCHED() __builtin_amdgcn_sched_barrier(0)
; template <int EPI, int MB, int NB> ...
;     ...
;   } else if constexpr (EPI == EPI_RES) {
;     const float* res = brow < e.res_split ? e.res0 + (size_t)brow * DM : e.res1 + (size_t)(brow - e.res_split) * DM;
;     const bool rb = e.resb != nullptr;
; #pragma unroll
;     for (int m = 0; m < MB; ++m) {
;       const int lr = lrow0 + m * 16;
;       float sq = 0.f;
;       u32x2 ob[2], rw[2];
;       if (rb) unwiden16(*(const i32x4*)(e.resb + (size_t)(brow + lr) * DM + colw), rw[0], rw[1]);
; #pragma unroll
;       for (int n = 0; n < NB; ++n) {
;         const int col = col0 + n * 16;
;         float4 r4;
;         if (rb) {
;           const u32x2 rr = rw[n];
;           r4.x = __uint_as_float(rr[0] << 16); r4.y = __uint_as_float(rr[0] & 0xffff0000u);
;           r4.z = __uint_as_float(rr[1] << 16); r4.w = __uint_as_float(rr[1] & 0xffff0000u);
;         } else {
;           r4 = *(const float4*)(res + (size_t)lr * DM + col);
;         }
;         float4 v;
;         v.x = r4.x + e.alpha * acc[m][n][0]; v.y = r4.y + e.alpha * acc[m][n][1];
;         v.z = r4.z + e.alpha * acc[m][n][2]; v.w = r4.w + e.alpha * acc[m][n][3];
;         ob[n][0] = pk_bf16(v.x, v.y); ob[n][1] = pk_bf16(v.z, v.w);
;         sq += v.x * v.x + v.y * v.y + v.z * v.z + v.w * v.w;
;       }
;       *(i32x4*)(e.o16 + (size_t)(brow + lr) * DM + colw) = widen16(ob[0], ob[1]);
;       sq += __shfl_xor(sq, 16); sq += __shfl_xor(sq, 32);
;       if (fq == 0) s_part[part_slot * 256 + lr] = sq;
;       SCHED();
;     }
.LBB0_134:
	s_or_b64 exec, exec, s[48:49]
	v_add_u32_e32 v116, 32, v132
	v_ashrrev_i32_e32 v117, 31, v116
	s_waitcnt lgkmcnt(0)
	v_lshlrev_b64 v[112:113], 13, v[116:117]
	v_lshl_add_u64 v[112:113], s[10:11], 0, v[112:113]
	v_lshl_add_u64 v[118:119], v[130:131], 2, v[112:113]
	v_mov_b32_e32 v252, 0x20000
	v_mov_b32_e32 v253, 0
	global_load_dwordx4 v[232:235], v[118:119], off
	global_load_dwordx4 v[236:239], v[118:119], off offset:64
	v_lshl_add_u64 v[248:249], v[118:119], 0, v[252:253]
	global_load_dwordx4 v[240:243], v[248:249], off
	global_load_dwordx4 v[244:247], v[248:249], off offset:64
	s_waitcnt vmcnt(3)
	v_mov_b32_e32 v112, v232
	v_mov_b32_e32 v113, v233
	v_mov_b32_e32 v114, v234
	v_mov_b32_e32 v115, v235
	v_pk_fma_f32 v[112:113], v[108:109], 0.5, v[112:113] op_sel_hi:[1,0,1]
	v_pk_fma_f32 v[110:111], v[110:111], 0.5, v[114:115] op_sel_hi:[1,0,1]
	v_cvt_pk_bf16_f32 v108, v112, v113
	v_cvt_pk_bf16_f32 v109, v110, v111
	v_pk_mul_f32 v[114:115], v[112:113], v[112:113]
	v_pk_mul_f32 v[122:123], v[110:111], v[110:111]
	s_waitcnt vmcnt(2)
	v_mov_b32_e32 v110, v236
	v_mov_b32_e32 v111, v237
	v_mov_b32_e32 v112, v238
	v_mov_b32_e32 v113, v239
	v_pk_fma_f32 v[104:105], v[104:105], 0.5, v[110:111] op_sel_hi:[1,0,1]
	v_pk_fma_f32 v[106:107], v[106:107], 0.5, v[112:113] op_sel_hi:[1,0,1]
	v_cvt_pk_bf16_f32 v110, v104, v105
	v_pk_mul_f32 v[104:105], v[104:105], v[104:105]
	v_cvt_pk_bf16_f32 v111, v106, v107
	v_pk_mul_f32 v[106:107], v[106:107], v[106:107]
	v_add_f32_e32 v104, v104, v105
	v_add_f32_e32 v105, v114, v115
	v_add_f32_e32 v104, v106, v104
	v_add_f32_e32 v105, v122, v105
	v_add_f32_e32 v104, v107, v104
	v_add_f32_e32 v105, v123, v105
	v_add_f32_e32 v106, v105, v104
	v_add_u32_e32 v104, s1, v116
	v_ashrrev_i32_e32 v105, 31, v104
	v_lshlrev_b64 v[104:105], 12, v[104:105]
	v_lshl_add_u64 v[104:105], s[54:55], 0, v[104:105]
	v_permlane16_swap_b32_e32 v108, v110
	v_permlane16_swap_b32_e32 v109, v111
	v_lshl_add_u64 v[104:105], v[128:129], 1, v[104:105]
	global_store_dwordx4 v[104:105], v[108:111], off
	ds_bpermute_b32 v104, v135, v106
	s_waitcnt lgkmcnt(0)
	v_add_f32_e32 v104, v106, v104
	ds_bpermute_b32 v105, v134, v104
	s_and_saveexec_b64 s[48:49], s[8:9]
	s_cbranch_execz .LBB0_136
	s_waitcnt lgkmcnt(0)
	v_add_f32_e32 v104, v104, v105
	ds_write_b32 v120, v104 offset:128
.LBB0_136:
	s_or_b64 exec, exec, s[48:49]
	v_add_u32_e32 v108, 48, v132
	v_ashrrev_i32_e32 v109, 31, v108
	s_waitcnt lgkmcnt(0)
	v_lshlrev_b64 v[104:105], 13, v[108:109]
	v_lshl_add_u64 v[104:105], s[10:11], 0, v[104:105]
	v_lshl_add_u64 v[110:111], v[130:131], 2, v[104:105]
	s_waitcnt vmcnt(2)
	v_mov_b32_e32 v104, v240
	v_mov_b32_e32 v105, v241
	v_mov_b32_e32 v106, v242
	v_mov_b32_e32 v107, v243
	v_pk_fma_f32 v[104:105], v[100:101], 0.5, v[104:105] op_sel_hi:[1,0,1]
	v_pk_fma_f32 v[102:103], v[102:103], 0.5, v[106:107] op_sel_hi:[1,0,1]
	v_cvt_pk_bf16_f32 v100, v104, v105
	v_cvt_pk_bf16_f32 v101, v102, v103
	v_pk_mul_f32 v[106:107], v[104:105], v[104:105]
	v_pk_mul_f32 v[112:113], v[102:103], v[102:103]
	s_waitcnt vmcnt(1)
	v_mov_b32_e32 v102, v244
	v_mov_b32_e32 v103, v245
	v_mov_b32_e32 v104, v246
	v_mov_b32_e32 v105, v247
	v_pk_fma_f32 v[96:97], v[96:97], 0.5, v[102:103] op_sel_hi:[1,0,1]
	v_pk_fma_f32 v[98:99], v[98:99], 0.5, v[104:105] op_sel_hi:[1,0,1]
	v_cvt_pk_bf16_f32 v102, v96, v97
	v_pk_mul_f32 v[96:97], v[96:97], v[96:97]
	v_cvt_pk_bf16_f32 v103, v98, v99
	v_pk_mul_f32 v[98:99], v[98:99], v[98:99]
	v_add_f32_e32 v96, v96, v97
	v_add_f32_e32 v97, v106, v107
	v_add_f32_e32 v96, v98, v96
	v_add_f32_e32 v97, v112, v97
	v_add_f32_e32 v96, v99, v96
	v_add_f32_e32 v97, v113, v97
	v_add_f32_e32 v98, v97, v96
	v_add_u32_e32 v96, s1, v108
	v_ashrrev_i32_e32 v97, 31, v96
	v_lshlrev_b64 v[96:97], 12, v[96:97]
	v_lshl_add_u64 v[96:97], s[54:55], 0, v[96:97]
	v_permlane16_swap_b32_e32 v100, v102
	v_permlane16_swap_b32_e32 v101, v103
	v_lshl_add_u64 v[96:97], v[128:129], 1, v[96:97]
	global_store_dwordx4 v[96:97], v[100:103], off
	ds_bpermute_b32 v96, v135, v98
	s_waitcnt lgkmcnt(0)
	v_add_f32_e32 v96, v98, v96
	ds_bpermute_b32 v97, v134, v96
	s_and_saveexec_b64 s[48:49], s[8:9]
	s_cbranch_execz .LBB0_138
	s_waitcnt lgkmcnt(0)
	v_add_f32_e32 v96, v96, v97
	ds_write_b32 v120, v96 offset:192
.LBB0_138:
	s_or_b64 exec, exec, s[48:49]
	v_mov_b32_e32 v100, v209
	v_mov_b32_e32 v96, v212
	s_nop 0
	v_ashrrev_i32_e32 v101, 31, v100
	v_add_u32_e32 v98, s65, v96
	v_lshlrev_b64 v[102:103], 13, v[100:101]
	v_lshl_add_u64 v[102:103], s[10:11], 0, v[102:103]
	v_ashrrev_i32_e32 v99, 31, v98
	v_lshl_add_u64 v[106:107], v[98:99], 2, v[102:103]
	v_mov_b32_e32 v252, 0x20000
	v_mov_b32_e32 v253, 0
	global_load_dwordx4 v[232:235], v[106:107], off
	global_load_dwordx4 v[236:239], v[106:107], off offset:64
	v_lshl_add_u64 v[248:249], v[106:107], 0, v[252:253]
	global_load_dwordx4 v[240:243], v[248:249], off
	global_load_dwordx4 v[244:247], v[248:249], off offset:64
	v_add_u32_e32 v96, v98, v211
	s_waitcnt lgkmcnt(0)
	v_ashrrev_i32_e32 v97, 31, v96
	s_waitcnt vmcnt(3)
	v_mov_b32_e32 v102, v232
	v_mov_b32_e32 v103, v233
	v_mov_b32_e32 v104, v234
	v_mov_b32_e32 v105, v235
	v_pk_fma_f32 v[102:103], v[92:93], 0.5, v[102:103] op_sel_hi:[1,0,1]
	v_pk_fma_f32 v[94:95], v[94:95], 0.5, v[104:105] op_sel_hi:[1,0,1]
	v_cvt_pk_bf16_f32 v92, v102, v103
	v_pk_mul_f32 v[108:109], v[102:103], v[102:103]
	v_cvt_pk_bf16_f32 v93, v94, v95
	v_pk_mul_f32 v[110:111], v[94:95], v[94:95]
	s_waitcnt vmcnt(2)
	v_mov_b32_e32 v102, v236
	v_mov_b32_e32 v103, v237
	v_mov_b32_e32 v104, v238
	v_mov_b32_e32 v105, v239
	v_pk_fma_f32 v[88:89], v[88:89], 0.5, v[102:103] op_sel_hi:[1,0,1]
	v_pk_fma_f32 v[90:91], v[90:91], 0.5, v[104:105] op_sel_hi:[1,0,1]
	v_cvt_pk_bf16_f32 v94, v88, v89
	v_pk_mul_f32 v[88:89], v[88:89], v[88:89]
	v_cvt_pk_bf16_f32 v95, v90, v91
	v_pk_mul_f32 v[90:91], v[90:91], v[90:91]
	v_add_f32_e32 v88, v88, v89
	v_add_f32_e32 v89, v108, v109
	v_add_f32_e32 v88, v90, v88
	v_add_f32_e32 v89, v110, v89
	v_add_f32_e32 v88, v91, v88
	v_add_f32_e32 v89, v111, v89
	v_add_f32_e32 v90, v89, v88
	v_add_u32_e32 v88, s1, v100
	v_ashrrev_i32_e32 v89, 31, v88
	v_lshlrev_b64 v[88:89], 12, v[88:89]
	v_lshl_add_u64 v[88:89], s[54:55], 0, v[88:89]
	v_permlane16_swap_b32_e32 v92, v94
	v_permlane16_swap_b32_e32 v93, v95
	v_lshl_add_u64 v[88:89], v[96:97], 1, v[88:89]
	global_store_dwordx4 v[88:89], v[92:95], off
	ds_bpermute_b32 v88, v135, v90
	s_waitcnt lgkmcnt(0)
	v_add_f32_e32 v89, v90, v88
	ds_bpermute_b32 v90, v134, v89
	v_lshl_add_u32 v88, v100, 2, s16
	s_and_saveexec_b64 s[48:49], s[8:9]
	s_cbranch_execz .LBB0_140
	s_waitcnt lgkmcnt(0)
	v_add_f32_e32 v89, v89, v90
	ds_write_b32 v88, v89 offset:4096
; #define SCHED() __builtin_amdgcn_sched_barrier(0)
; template <int EPI, int MB, int NB> ...
;     ...
;   } else if constexpr (EPI == EPI_RES) {
;     const float* res = brow < e.res_split ? e.res0 + (size_t)brow * DM : e.res1 + (size_t)(brow - e.res_split) * DM;
;     const bool rb = e.resb != nullptr;
; #pragma unroll
;     for (int m = 0; m < MB; ++m) {
;       const int lr = lrow0 + m * 16;
;       float sq = 0.f;
;       u32x2 ob[2], rw[2];
;       if (rb) unwiden16(*(const i32x4*)(e.resb + (size_t)(brow + lr) * DM + colw), rw[0], rw[1]);
; #pragma unroll
;       for (int n = 0; n < NB; ++n) {
;         const int col = col0 + n * 16;
;         float4 r4;
;         if (rb) {
;           const u32x2 rr = rw[n];
;           r4.x = __uint_as_float(rr[0] << 16); r4.y = __uint_as_float(rr[0] & 0xffff0000u);
;           r4.z = __uint_as_float(rr[1] << 16); r4.w = __uint_as_float(rr[1] & 0xffff0000u);
;         } else {
;           r4 = *(const float4*)(res + (size_t)lr * DM + col);
;         }
;         float4 v;
;         v.x = r4.x + e.alpha * acc[m][n][0]; v.y = r4.y + e.alpha * acc[m][n][1];
;         v.z = r4.z + e.alpha * acc[m][n][2]; v.w = r4.w + e.alpha * acc[m][n][3];
;         ob[n][0] = pk_bf16(v.x, v.y); ob[n][1] = pk_bf16(v.z, v.w);
;         sq += v.x * v.x + v.y * v.y + v.z * v.z + v.w * v.w;
;       }
;       *(i32x4*)(e.o16 + (size_t)(brow + lr) * DM + colw) = widen16(ob[0], ob[1]);
;       sq += __shfl_xor(sq, 16); sq += __shfl_xor(sq, 32);
;       if (fq == 0) s_part[part_slot * 256 + lr] = sq;
;       SCHED();
;     }
.LBB0_140:
	s_or_b64 exec, exec, s[48:49]
	v_add_u32_e32 v94, 16, v100
	v_ashrrev_i32_e32 v95, 31, v94
	s_waitcnt lgkmcnt(0)
	v_lshlrev_b64 v[90:91], 13, v[94:95]
	v_lshl_add_u64 v[90:91], s[10:11], 0, v[90:91]
	v_lshl_add_u64 v[102:103], v[98:99], 2, v[90:91]
	s_waitcnt vmcnt(2)
	v_mov_b32_e32 v90, v240
	v_mov_b32_e32 v91, v241
	v_mov_b32_e32 v92, v242
	v_mov_b32_e32 v93, v243
	v_pk_fma_f32 v[90:91], v[84:85], 0.5, v[90:91] op_sel_hi:[1,0,1]
	v_pk_fma_f32 v[86:87], v[86:87], 0.5, v[92:93] op_sel_hi:[1,0,1]
	v_cvt_pk_bf16_f32 v84, v90, v91
	v_pk_mul_f32 v[104:105], v[90:91], v[90:91]
	v_cvt_pk_bf16_f32 v85, v86, v87
	v_pk_mul_f32 v[106:107], v[86:87], v[86:87]
	s_waitcnt vmcnt(1)
	v_mov_b32_e32 v90, v244
	v_mov_b32_e32 v91, v245
	v_mov_b32_e32 v92, v246
	v_mov_b32_e32 v93, v247
	v_pk_fma_f32 v[80:81], v[80:81], 0.5, v[90:91] op_sel_hi:[1,0,1]
	v_pk_fma_f32 v[82:83], v[82:83], 0.5, v[92:93] op_sel_hi:[1,0,1]
	v_cvt_pk_bf16_f32 v86, v80, v81
	v_pk_mul_f32 v[80:81], v[80:81], v[80:81]
	v_cvt_pk_bf16_f32 v87, v82, v83
	v_pk_mul_f32 v[82:83], v[82:83], v[82:83]
	v_add_f32_e32 v80, v80, v81
	v_add_f32_e32 v81, v104, v105
	v_add_f32_e32 v80, v82, v80
	v_add_f32_e32 v81, v106, v81
	v_add_f32_e32 v80, v83, v80
	v_add_f32_e32 v81, v107, v81
	v_add_f32_e32 v82, v81, v80
	v_add_u32_e32 v80, s1, v94
	v_ashrrev_i32_e32 v81, 31, v80
	v_lshlrev_b64 v[80:81], 12, v[80:81]
	v_lshl_add_u64 v[80:81], s[54:55], 0, v[80:81]
	v_permlane16_swap_b32_e32 v84, v86
	v_permlane16_swap_b32_e32 v85, v87
	v_lshl_add_u64 v[80:81], v[96:97], 1, v[80:81]
	global_store_dwordx4 v[80:81], v[84:87], off
	ds_bpermute_b32 v80, v135, v82
	s_waitcnt lgkmcnt(0)
	v_add_f32_e32 v80, v82, v80
	ds_bpermute_b32 v81, v134, v80
	s_and_saveexec_b64 s[48:49], s[8:9]
	s_cbranch_execz .LBB0_142
	s_waitcnt lgkmcnt(0)
	v_add_f32_e32 v80, v80, v81
	ds_write_b32 v88, v80 offset:4160
.LBB0_142:
	s_or_b64 exec, exec, s[48:49]
	v_add_u32_e32 v84, 32, v100
	v_ashrrev_i32_e32 v85, 31, v84
	s_waitcnt lgkmcnt(0)
	v_lshlrev_b64 v[80:81], 13, v[84:85]
	v_lshl_add_u64 v[80:81], s[10:11], 0, v[80:81]
	v_lshl_add_u64 v[86:87], v[98:99], 2, v[80:81]
	v_mov_b32_e32 v252, 0x20000
	v_mov_b32_e32 v253, 0
	global_load_dwordx4 v[232:235], v[86:87], off
	global_load_dwordx4 v[236:239], v[86:87], off offset:64
	v_lshl_add_u64 v[248:249], v[86:87], 0, v[252:253]
	global_load_dwordx4 v[240:243], v[248:249], off
	global_load_dwordx4 v[244:247], v[248:249], off offset:64
	s_waitcnt vmcnt(3)
	v_mov_b32_e32 v80, v232
	v_mov_b32_e32 v81, v233
	v_mov_b32_e32 v82, v234
	v_mov_b32_e32 v83, v235
	v_pk_fma_f32 v[80:81], v[76:77], 0.5, v[80:81] op_sel_hi:[1,0,1]
	v_pk_fma_f32 v[78:79], v[78:79], 0.5, v[82:83] op_sel_hi:[1,0,1]
	v_cvt_pk_bf16_f32 v76, v80, v81
	v_cvt_pk_bf16_f32 v77, v78, v79
	v_pk_mul_f32 v[82:83], v[80:81], v[80:81]
	v_pk_mul_f32 v[90:91], v[78:79], v[78:79]
	s_waitcnt vmcnt(2)
	v_mov_b32_e32 v78, v236
	v_mov_b32_e32 v79, v237
	v_mov_b32_e32 v80, v238
	v_mov_b32_e32 v81, v239
	v_pk_fma_f32 v[72:73], v[72:73], 0.5, v[78:79] op_sel_hi:[1,0,1]
	v_pk_fma_f32 v[74:75], v[74:75], 0.5, v[80:81] op_sel_hi:[1,0,1]
	v_cvt_pk_bf16_f32 v78, v72, v73
	v_pk_mul_f32 v[72:73], v[72:73], v[72:73]
	v_cvt_pk_bf16_f32 v79, v74, v75
	v_pk_mul_f32 v[74:75], v[74:75], v[74:75]
	v_add_f32_e32 v72, v72, v73
	v_add_f32_e32 v73, v82, v83
	v_add_f32_e32 v72, v74, v72
	v_add_f32_e32 v73, v90, v73
	v_add_f32_e32 v72, v75, v72
	v_add_f32_e32 v73, v91, v73
	v_add_f32_e32 v74, v73, v72
	v_add_u32_e32 v72, s1, v84
	v_ashrrev_i32_e32 v73, 31, v72
	v_lshlrev_b64 v[72:73], 12, v[72:73]
	v_lshl_add_u64 v[72:73], s[54:55], 0, v[72:73]
	v_permlane16_swap_b32_e32 v76, v78
	v_permlane16_swap_b32_e32 v77, v79
	v_lshl_add_u64 v[72:73], v[96:97], 1, v[72:73]
	global_store_dwordx4 v[72:73], v[76:79], off
	ds_bpermute_b32 v72, v135, v74
	s_waitcnt lgkmcnt(0)
	v_add_f32_e32 v72, v74, v72
	ds_bpermute_b32 v73, v134, v72
	s_and_saveexec_b64 s[48:49], s[8:9]
	s_cbranch_execz .LBB0_144
	s_waitcnt lgkmcnt(0)
	v_add_f32_e32 v72, v72, v73
	ds_write_b32 v88, v72 offset:4224
.LBB0_144:
	s_or_b64 exec, exec, s[48:49]
	v_add_u32_e32 v76, 48, v100
	v_ashrrev_i32_e32 v77, 31, v76
	s_waitcnt lgkmcnt(0)
	v_lshlrev_b64 v[72:73], 13, v[76:77]
	v_lshl_add_u64 v[72:73], s[10:11], 0, v[72:73]
	v_lshl_add_u64 v[78:79], v[98:99], 2, v[72:73]
	s_waitcnt vmcnt(2)
	v_mov_b32_e32 v72, v240
	v_mov_b32_e32 v73, v241
	v_mov_b32_e32 v74, v242
	v_mov_b32_e32 v75, v243
	v_pk_fma_f32 v[72:73], v[68:69], 0.5, v[72:73] op_sel_hi:[1,0,1]
	v_pk_fma_f32 v[70:71], v[70:71], 0.5, v[74:75] op_sel_hi:[1,0,1]
	v_cvt_pk_bf16_f32 v68, v72, v73
	v_cvt_pk_bf16_f32 v69, v70, v71
	v_pk_mul_f32 v[74:75], v[72:73], v[72:73]
	v_pk_mul_f32 v[80:81], v[70:71], v[70:71]
	s_waitcnt vmcnt(1)
	v_mov_b32_e32 v70, v244
	v_mov_b32_e32 v71, v245
	v_mov_b32_e32 v72, v246
	v_mov_b32_e32 v73, v247
	v_pk_fma_f32 v[64:65], v[64:65], 0.5, v[70:71] op_sel_hi:[1,0,1]
	v_pk_fma_f32 v[66:67], v[66:67], 0.5, v[72:73] op_sel_hi:[1,0,1]
	v_cvt_pk_bf16_f32 v70, v64, v65
	v_pk_mul_f32 v[64:65], v[64:65], v[64:65]
	v_cvt_pk_bf16_f32 v71, v66, v67
	v_pk_mul_f32 v[66:67], v[66:67], v[66:67]
	v_add_f32_e32 v64, v64, v65
	v_add_f32_e32 v65, v74, v75
	v_add_f32_e32 v64, v66, v64
	v_add_f32_e32 v65, v80, v65
	v_add_f32_e32 v64, v67, v64
	v_add_f32_e32 v65, v81, v65
	v_add_f32_e32 v66, v65, v64
	v_add_u32_e32 v64, s1, v76
	v_ashrrev_i32_e32 v65, 31, v64
	v_lshlrev_b64 v[64:65], 12, v[64:65]
	v_lshl_add_u64 v[64:65], s[54:55], 0, v[64:65]
	v_permlane16_swap_b32_e32 v68, v70
	v_permlane16_swap_b32_e32 v69, v71
	v_lshl_add_u64 v[64:65], v[96:97], 1, v[64:65]
	global_store_dwordx4 v[64:65], v[68:71], off
	ds_bpermute_b32 v64, v135, v66
	s_waitcnt lgkmcnt(0)
	v_add_f32_e32 v64, v66, v64
	ds_bpermute_b32 v65, v134, v64
	s_and_saveexec_b64 s[48:49], s[8:9]
	s_cbranch_execz .LBB0_146
	s_waitcnt lgkmcnt(0)
	v_add_f32_e32 v64, v64, v65
	ds_write_b32 v88, v64 offset:4288
; #define SCHED() __builtin_amdgcn_sched_barrier(0)
; template <int EPI, int MB, int NB> ...
;     ...
;   } else if constexpr (EPI == EPI_RES) {
;     const float* res = brow < e.res_split ? e.res0 + (size_t)brow * DM : e.res1 + (size_t)(brow - e.res_split) * DM;
;     const bool rb = e.resb != nullptr;
; #pragma unroll
;     for (int m = 0; m < MB; ++m) {
;       const int lr = lrow0 + m * 16;
;       float sq = 0.f;
;       u32x2 ob[2], rw[2];
;       if (rb) unwiden16(*(const i32x4*)(e.resb + (size_t)(brow + lr) * DM + colw), rw[0], rw[1]);
; #pragma unroll
;       for (int n = 0; n < NB; ++n) {
;         const int col = col0 + n * 16;
;         float4 r4;
;         if (rb) {
;           const u32x2 rr = rw[n];
;           r4.x = __uint_as_float(rr[0] << 16); r4.y = __uint_as_float(rr[0] & 0xffff0000u);
;           r4.z = __uint_as_float(rr[1] << 16); r4.w = __uint_as_float(rr[1] & 0xffff0000u);
;         } else {
;           r4 = *(const float4*)(res + (size_t)lr * DM + col);
;         }
;         float4 v;
;         v.x = r4.x + e.alpha * acc[m][n][0]; v.y = r4.y + e.alpha * acc[m][n][1];
;         v.z = r4.z + e.alpha * acc[m][n][2]; v.w = r4.w + e.alpha * acc[m][n][3];
;         ob[n][0] = pk_bf16(v.x, v.y); ob[n][1] = pk_bf16(v.z, v.w);
;         sq += v.x * v.x + v.y * v.y + v.z * v.z + v.w * v.w;
;       }
;       *(i32x4*)(e.o16 + (size_t)(brow + lr) * DM + colw) = widen16(ob[0], ob[1]);
;       sq += __shfl_xor(sq, 16); sq += __shfl_xor(sq, 32);
;       if (fq == 0) s_part[part_slot * 256 + lr] = sq;
;       SCHED();
;     }
.LBB0_146:
	s_or_b64 exec, exec, s[48:49]
	v_mov_b32_e32 v64, v210
	v_mov_b32_e32 v68, v213
	s_nop 0
	v_ashrrev_i32_e32 v69, 31, v68
	v_add_u32_e32 v66, s65, v64
	v_lshlrev_b64 v[70:71], 13, v[68:69]
	v_lshl_add_u64 v[70:71], s[10:11], 0, v[70:71]
	v_ashrrev_i32_e32 v67, 31, v66
	v_lshl_add_u64 v[74:75], v[66:67], 2, v[70:71]
	v_mov_b32_e32 v252, 0x20000
	v_mov_b32_e32 v253, 0
	global_load_dwordx4 v[232:235], v[74:75], off
	global_load_dwordx4 v[236:239], v[74:75], off offset:64
	v_lshl_add_u64 v[248:249], v[74:75], 0, v[252:253]
	global_load_dwordx4 v[240:243], v[248:249], off
	global_load_dwordx4 v[244:247], v[248:249], off offset:64
	v_add_u32_e32 v64, v66, v211
	s_waitcnt lgkmcnt(0)
	v_ashrrev_i32_e32 v65, 31, v64
	s_waitcnt vmcnt(3)
	v_mov_b32_e32 v70, v232
	v_mov_b32_e32 v71, v233
	v_mov_b32_e32 v72, v234
	v_mov_b32_e32 v73, v235
	v_pk_fma_f32 v[70:71], v[60:61], 0.5, v[70:71] op_sel_hi:[1,0,1]
	v_pk_fma_f32 v[62:63], v[62:63], 0.5, v[72:73] op_sel_hi:[1,0,1]
	v_cvt_pk_bf16_f32 v60, v70, v71
	v_pk_mul_f32 v[76:77], v[70:71], v[70:71]
	v_cvt_pk_bf16_f32 v61, v62, v63
	v_pk_mul_f32 v[78:79], v[62:63], v[62:63]
	s_waitcnt vmcnt(2)
	v_mov_b32_e32 v70, v236
	v_mov_b32_e32 v71, v237
	v_mov_b32_e32 v72, v238
	v_mov_b32_e32 v73, v239
	v_pk_fma_f32 v[56:57], v[56:57], 0.5, v[70:71] op_sel_hi:[1,0,1]
	v_pk_fma_f32 v[58:59], v[58:59], 0.5, v[72:73] op_sel_hi:[1,0,1]
	v_cvt_pk_bf16_f32 v62, v56, v57
	v_pk_mul_f32 v[56:57], v[56:57], v[56:57]
	v_cvt_pk_bf16_f32 v63, v58, v59
	v_pk_mul_f32 v[58:59], v[58:59], v[58:59]
	v_add_f32_e32 v56, v56, v57
	v_add_f32_e32 v57, v76, v77
	v_add_f32_e32 v56, v58, v56
	v_add_f32_e32 v57, v78, v57
	v_add_f32_e32 v56, v59, v56
	v_add_f32_e32 v57, v79, v57
	v_add_f32_e32 v58, v57, v56
	v_add_u32_e32 v56, s1, v68
	v_ashrrev_i32_e32 v57, 31, v56
	v_lshlrev_b64 v[56:57], 12, v[56:57]
	v_lshl_add_u64 v[56:57], s[54:55], 0, v[56:57]
	v_permlane16_swap_b32_e32 v60, v62
	v_permlane16_swap_b32_e32 v61, v63
	v_lshl_add_u64 v[56:57], v[64:65], 1, v[56:57]
	global_store_dwordx4 v[56:57], v[60:63], off
	ds_bpermute_b32 v56, v135, v58
	s_waitcnt lgkmcnt(0)
	v_add_f32_e32 v57, v58, v56
	ds_bpermute_b32 v58, v134, v57
	v_lshl_add_u32 v56, v68, 2, s16
	s_and_saveexec_b64 s[48:49], s[8:9]
	s_cbranch_execz .LBB0_148
	s_waitcnt lgkmcnt(0)
	v_add_f32_e32 v57, v57, v58
	ds_write_b32 v56, v57
.LBB0_148:
	s_or_b64 exec, exec, s[48:49]
	v_add_u32_e32 v62, 16, v68
	v_ashrrev_i32_e32 v63, 31, v62
	s_waitcnt lgkmcnt(0)
	v_lshlrev_b64 v[58:59], 13, v[62:63]
	v_lshl_add_u64 v[58:59], s[10:11], 0, v[58:59]
	v_lshl_add_u64 v[70:71], v[66:67], 2, v[58:59]
	s_waitcnt vmcnt(2)
	v_mov_b32_e32 v58, v240
	v_mov_b32_e32 v59, v241
	v_mov_b32_e32 v60, v242
	v_mov_b32_e32 v61, v243
	v_pk_fma_f32 v[58:59], v[52:53], 0.5, v[58:59] op_sel_hi:[1,0,1]
	v_pk_fma_f32 v[54:55], v[54:55], 0.5, v[60:61] op_sel_hi:[1,0,1]
	v_cvt_pk_bf16_f32 v52, v58, v59
	v_pk_mul_f32 v[72:73], v[58:59], v[58:59]
	v_cvt_pk_bf16_f32 v53, v54, v55
	v_pk_mul_f32 v[74:75], v[54:55], v[54:55]
	s_waitcnt vmcnt(1)
	v_mov_b32_e32 v58, v244
	v_mov_b32_e32 v59, v245
	v_mov_b32_e32 v60, v246
	v_mov_b32_e32 v61, v247
	v_pk_fma_f32 v[48:49], v[48:49], 0.5, v[58:59] op_sel_hi:[1,0,1]
	v_pk_fma_f32 v[50:51], v[50:51], 0.5, v[60:61] op_sel_hi:[1,0,1]
	v_cvt_pk_bf16_f32 v54, v48, v49
	v_pk_mul_f32 v[48:49], v[48:49], v[48:49]
	v_cvt_pk_bf16_f32 v55, v50, v51
	v_pk_mul_f32 v[50:51], v[50:51], v[50:51]
	v_add_f32_e32 v48, v48, v49
	v_add_f32_e32 v49, v72, v73
	v_add_f32_e32 v48, v50, v48
	v_add_f32_e32 v49, v74, v49
	v_add_f32_e32 v48, v51, v48
	v_add_f32_e32 v49, v75, v49
	v_add_f32_e32 v50, v49, v48
	v_add_u32_e32 v48, s1, v62
	v_ashrrev_i32_e32 v49, 31, v48
	v_lshlrev_b64 v[48:49], 12, v[48:49]
	v_lshl_add_u64 v[48:49], s[54:55], 0, v[48:49]
	v_permlane16_swap_b32_e32 v52, v54
	v_permlane16_swap_b32_e32 v53, v55
	v_lshl_add_u64 v[48:49], v[64:65], 1, v[48:49]
	global_store_dwordx4 v[48:49], v[52:55], off
	ds_bpermute_b32 v48, v135, v50
	s_waitcnt lgkmcnt(0)
	v_add_f32_e32 v48, v50, v48
	ds_bpermute_b32 v49, v134, v48
	s_and_saveexec_b64 s[48:49], s[8:9]
	s_cbranch_execz .LBB0_150
	s_waitcnt lgkmcnt(0)
	v_add_f32_e32 v48, v48, v49
	ds_write_b32 v56, v48 offset:64
.LBB0_150:
	s_or_b64 exec, exec, s[48:49]
	v_add_u32_e32 v52, 32, v68
	v_ashrrev_i32_e32 v53, 31, v52
	s_waitcnt lgkmcnt(0)
	v_lshlrev_b64 v[48:49], 13, v[52:53]
	v_lshl_add_u64 v[48:49], s[10:11], 0, v[48:49]
	v_lshl_add_u64 v[54:55], v[66:67], 2, v[48:49]
	v_mov_b32_e32 v252, 0x20000
	v_mov_b32_e32 v253, 0
	global_load_dwordx4 v[232:235], v[54:55], off
	global_load_dwordx4 v[236:239], v[54:55], off offset:64
	v_lshl_add_u64 v[248:249], v[54:55], 0, v[252:253]
	global_load_dwordx4 v[240:243], v[248:249], off
	global_load_dwordx4 v[244:247], v[248:249], off offset:64
	s_waitcnt vmcnt(3)
	v_mov_b32_e32 v48, v232
	v_mov_b32_e32 v49, v233
	v_mov_b32_e32 v50, v234
	v_mov_b32_e32 v51, v235
	v_pk_fma_f32 v[48:49], v[44:45], 0.5, v[48:49] op_sel_hi:[1,0,1]
	v_pk_fma_f32 v[46:47], v[46:47], 0.5, v[50:51] op_sel_hi:[1,0,1]
	v_cvt_pk_bf16_f32 v44, v48, v49
	v_cvt_pk_bf16_f32 v45, v46, v47
	v_pk_mul_f32 v[50:51], v[48:49], v[48:49]
	v_pk_mul_f32 v[58:59], v[46:47], v[46:47]
	s_waitcnt vmcnt(2)
	v_mov_b32_e32 v46, v236
	v_mov_b32_e32 v47, v237
	v_mov_b32_e32 v48, v238
	v_mov_b32_e32 v49, v239
	v_pk_fma_f32 v[40:41], v[40:41], 0.5, v[46:47] op_sel_hi:[1,0,1]
	v_pk_fma_f32 v[42:43], v[42:43], 0.5, v[48:49] op_sel_hi:[1,0,1]
	v_cvt_pk_bf16_f32 v46, v40, v41
	v_pk_mul_f32 v[40:41], v[40:41], v[40:41]
	v_cvt_pk_bf16_f32 v47, v42, v43
	v_pk_mul_f32 v[42:43], v[42:43], v[42:43]
	v_add_f32_e32 v40, v40, v41
	v_add_f32_e32 v41, v50, v51
	v_add_f32_e32 v40, v42, v40
	v_add_f32_e32 v41, v58, v41
	v_add_f32_e32 v40, v43, v40
	v_add_f32_e32 v41, v59, v41
	v_add_f32_e32 v42, v41, v40
	v_add_u32_e32 v40, s1, v52
	v_ashrrev_i32_e32 v41, 31, v40
	v_lshlrev_b64 v[40:41], 12, v[40:41]
	v_lshl_add_u64 v[40:41], s[54:55], 0, v[40:41]
	v_permlane16_swap_b32_e32 v44, v46
	v_permlane16_swap_b32_e32 v45, v47
	v_lshl_add_u64 v[40:41], v[64:65], 1, v[40:41]
	global_store_dwordx4 v[40:41], v[44:47], off
	ds_bpermute_b32 v40, v135, v42
	s_waitcnt lgkmcnt(0)
	v_add_f32_e32 v40, v42, v40
	ds_bpermute_b32 v41, v134, v40
	s_and_saveexec_b64 s[48:49], s[8:9]
	s_cbranch_execz .LBB0_152
	s_waitcnt lgkmcnt(0)
	v_add_f32_e32 v40, v40, v41
	ds_write_b32 v56, v40 offset:128
; #define SCHED() __builtin_amdgcn_sched_barrier(0)
; template <int EPI, int MB, int NB> ...
;     ...
;   } else if constexpr (EPI == EPI_RES) {
;     const float* res = brow < e.res_split ? e.res0 + (size_t)brow * DM : e.res1 + (size_t)(brow - e.res_split) * DM;
;     const bool rb = e.resb != nullptr;
; #pragma unroll
;     for (int m = 0; m < MB; ++m) {
;       const int lr = lrow0 + m * 16;
;       float sq = 0.f;
;       u32x2 ob[2], rw[2];
;       if (rb) unwiden16(*(const i32x4*)(e.resb + (size_t)(brow + lr) * DM + colw), rw[0], rw[1]);
; #pragma unroll
;       for (int n = 0; n < NB; ++n) {
;         const int col = col0 + n * 16;
;         float4 r4;
;         if (rb) {
;           const u32x2 rr = rw[n];
;           r4.x = __uint_as_float(rr[0] << 16); r4.y = __uint_as_float(rr[0] & 0xffff0000u);
;           r4.z = __uint_as_float(rr[1] << 16); r4.w = __uint_as_float(rr[1] & 0xffff0000u);
;         } else {
;           r4 = *(const float4*)(res + (size_t)lr * DM + col);
;         }
;         float4 v;
;         v.x = r4.x + e.alpha * acc[m][n][0]; v.y = r4.y + e.alpha * acc[m][n][1];
;         v.z = r4.z + e.alpha * acc[m][n][2]; v.w = r4.w + e.alpha * acc[m][n][3];
;         ob[n][0] = pk_bf16(v.x, v.y); ob[n][1] = pk_bf16(v.z, v.w);
;         sq += v.x * v.x + v.y * v.y + v.z * v.z + v.w * v.w;
;       }
;       *(i32x4*)(e.o16 + (size_t)(brow + lr) * DM + colw) = widen16(ob[0], ob[1]);
;       sq += __shfl_xor(sq, 16); sq += __shfl_xor(sq, 32);
;       if (fq == 0) s_part[part_slot * 256 + lr] = sq;
;       SCHED();
;     }
.LBB0_152:
	s_or_b64 exec, exec, s[48:49]
	v_add_u32_e32 v44, 48, v68
	v_ashrrev_i32_e32 v45, 31, v44
	s_waitcnt lgkmcnt(0)
	v_lshlrev_b64 v[40:41], 13, v[44:45]
	v_lshl_add_u64 v[40:41], s[10:11], 0, v[40:41]
	v_lshl_add_u64 v[46:47], v[66:67], 2, v[40:41]
	s_waitcnt vmcnt(2)
	v_mov_b32_e32 v40, v240
	v_mov_b32_e32 v41, v241
	v_mov_b32_e32 v42, v242
	v_mov_b32_e32 v43, v243
	v_pk_fma_f32 v[40:41], v[36:37], 0.5, v[40:41] op_sel_hi:[1,0,1]
	v_pk_fma_f32 v[38:39], v[38:39], 0.5, v[42:43] op_sel_hi:[1,0,1]
	v_cvt_pk_bf16_f32 v36, v40, v41
	v_cvt_pk_bf16_f32 v37, v38, v39
	v_pk_mul_f32 v[42:43], v[40:41], v[40:41]
	v_pk_mul_f32 v[48:49], v[38:39], v[38:39]
	s_waitcnt vmcnt(1)
	v_mov_b32_e32 v38, v244
	v_mov_b32_e32 v39, v245
	v_mov_b32_e32 v40, v246
	v_mov_b32_e32 v41, v247
	v_pk_fma_f32 v[32:33], v[32:33], 0.5, v[38:39] op_sel_hi:[1,0,1]
	v_pk_fma_f32 v[34:35], v[34:35], 0.5, v[40:41] op_sel_hi:[1,0,1]
	v_cvt_pk_bf16_f32 v38, v32, v33
	v_pk_mul_f32 v[32:33], v[32:33], v[32:33]
	v_cvt_pk_bf16_f32 v39, v34, v35
	v_pk_mul_f32 v[34:35], v[34:35], v[34:35]
	v_add_f32_e32 v32, v32, v33
	v_add_f32_e32 v33, v42, v43
	v_add_f32_e32 v32, v34, v32
	v_add_f32_e32 v33, v48, v33
	v_add_f32_e32 v32, v35, v32
	v_add_f32_e32 v33, v49, v33
	v_add_f32_e32 v34, v33, v32
	v_add_u32_e32 v32, s1, v44
	v_ashrrev_i32_e32 v33, 31, v32
	v_lshlrev_b64 v[32:33], 12, v[32:33]
	v_lshl_add_u64 v[32:33], s[54:55], 0, v[32:33]
	v_permlane16_swap_b32_e32 v36, v38
	v_permlane16_swap_b32_e32 v37, v39
	v_lshl_add_u64 v[32:33], v[64:65], 1, v[32:33]
	global_store_dwordx4 v[32:33], v[36:39], off
	ds_bpermute_b32 v32, v135, v34
	s_waitcnt lgkmcnt(0)
	v_add_f32_e32 v32, v34, v32
	ds_bpermute_b32 v33, v134, v32
	s_and_saveexec_b64 s[48:49], s[8:9]
	s_cbranch_execz .LBB0_154
	s_waitcnt lgkmcnt(0)
	v_add_f32_e32 v32, v32, v33
	ds_write_b32 v56, v32 offset:192
.LBB0_154:
	s_or_b64 exec, exec, s[48:49]
	v_mov_b32_e32 v36, v213
	v_mov_b32_e32 v32, v212
	s_nop 0
	v_ashrrev_i32_e32 v37, 31, v36
	v_add_u32_e32 v34, s65, v32
	v_lshlrev_b64 v[38:39], 13, v[36:37]
	v_lshl_add_u64 v[38:39], s[10:11], 0, v[38:39]
	v_ashrrev_i32_e32 v35, 31, v34
	v_lshl_add_u64 v[42:43], v[34:35], 2, v[38:39]
	v_mov_b32_e32 v252, 0x20000
	v_mov_b32_e32 v253, 0
	global_load_dwordx4 v[232:235], v[42:43], off
	global_load_dwordx4 v[236:239], v[42:43], off offset:64
	v_lshl_add_u64 v[248:249], v[42:43], 0, v[252:253]
	global_load_dwordx4 v[240:243], v[248:249], off
	global_load_dwordx4 v[244:247], v[248:249], off offset:64
	v_add_u32_e32 v32, v34, v211
	s_waitcnt lgkmcnt(0)
	v_ashrrev_i32_e32 v33, 31, v32
	s_waitcnt vmcnt(3)
	v_mov_b32_e32 v38, v232
	v_mov_b32_e32 v39, v233
	v_mov_b32_e32 v40, v234
	v_mov_b32_e32 v41, v235
	v_pk_fma_f32 v[38:39], v[28:29], 0.5, v[38:39] op_sel_hi:[1,0,1]
	v_pk_fma_f32 v[30:31], v[30:31], 0.5, v[40:41] op_sel_hi:[1,0,1]
	v_cvt_pk_bf16_f32 v28, v38, v39
	v_pk_mul_f32 v[44:45], v[38:39], v[38:39]
	v_cvt_pk_bf16_f32 v29, v30, v31
	v_pk_mul_f32 v[46:47], v[30:31], v[30:31]
	s_waitcnt vmcnt(2)
	v_mov_b32_e32 v38, v236
	v_mov_b32_e32 v39, v237
	v_mov_b32_e32 v40, v238
	v_mov_b32_e32 v41, v239
	v_pk_fma_f32 v[24:25], v[24:25], 0.5, v[38:39] op_sel_hi:[1,0,1]
	v_pk_fma_f32 v[26:27], v[26:27], 0.5, v[40:41] op_sel_hi:[1,0,1]
	v_cvt_pk_bf16_f32 v30, v24, v25
	v_pk_mul_f32 v[24:25], v[24:25], v[24:25]
	v_cvt_pk_bf16_f32 v31, v26, v27
	v_pk_mul_f32 v[26:27], v[26:27], v[26:27]
	v_add_f32_e32 v24, v24, v25
	v_add_f32_e32 v25, v44, v45
	v_add_f32_e32 v24, v26, v24
	v_add_f32_e32 v25, v46, v25
	v_add_f32_e32 v24, v27, v24
	v_add_f32_e32 v25, v47, v25
	v_add_f32_e32 v26, v25, v24
	v_add_u32_e32 v24, s1, v36
	v_ashrrev_i32_e32 v25, 31, v24
	v_lshlrev_b64 v[24:25], 12, v[24:25]
	v_lshl_add_u64 v[24:25], s[54:55], 0, v[24:25]
	v_permlane16_swap_b32_e32 v28, v30
	v_permlane16_swap_b32_e32 v29, v31
	v_lshl_add_u64 v[24:25], v[32:33], 1, v[24:25]
	global_store_dwordx4 v[24:25], v[28:31], off
	ds_bpermute_b32 v24, v135, v26
	s_waitcnt lgkmcnt(0)
	v_add_f32_e32 v25, v26, v24
	ds_bpermute_b32 v26, v134, v25
	v_lshl_add_u32 v24, v36, 2, s16
	s_and_saveexec_b64 s[48:49], s[8:9]
	s_cbranch_execz .LBB0_156
	s_waitcnt lgkmcnt(0)
	v_add_f32_e32 v25, v25, v26
	ds_write_b32 v24, v25 offset:4096
; #define SCHED() __builtin_amdgcn_sched_barrier(0)
; template <int EPI, int MB, int NB> ...
;     ...
;   } else if constexpr (EPI == EPI_RES) {
;     const float* res = brow < e.res_split ? e.res0 + (size_t)brow * DM : e.res1 + (size_t)(brow - e.res_split) * DM;
;     const bool rb = e.resb != nullptr;
; #pragma unroll
;     for (int m = 0; m < MB; ++m) {
;       const int lr = lrow0 + m * 16;
;       float sq = 0.f;
;       u32x2 ob[2], rw[2];
;       if (rb) unwiden16(*(const i32x4*)(e.resb + (size_t)(brow + lr) * DM + colw), rw[0], rw[1]);
; #pragma unroll
;       for (int n = 0; n < NB; ++n) {
;         const int col = col0 + n * 16;
;         float4 r4;
;         if (rb) {
;           const u32x2 rr = rw[n];
;           r4.x = __uint_as_float(rr[0] << 16); r4.y = __uint_as_float(rr[0] & 0xffff0000u);
;           r4.z = __uint_as_float(rr[1] << 16); r4.w = __uint_as_float(rr[1] & 0xffff0000u);
;         } else {
;           r4 = *(const float4*)(res + (size_t)lr * DM + col);
;         }
;         float4 v;
;         v.x = r4.x + e.alpha * acc[m][n][0]; v.y = r4.y + e.alpha * acc[m][n][1];
;         v.z = r4.z + e.alpha * acc[m][n][2]; v.w = r4.w + e.alpha * acc[m][n][3];
;         ob[n][0] = pk_bf16(v.x, v.y); ob[n][1] = pk_bf16(v.z, v.w);
;         sq += v.x * v.x + v.y * v.y + v.z * v.z + v.w * v.w;
;       }
;       *(i32x4*)(e.o16 + (size_t)(brow + lr) * DM + colw) = widen16(ob[0], ob[1]);
;       sq += __shfl_xor(sq, 16); sq += __shfl_xor(sq, 32);
;       if (fq == 0) s_part[part_slot * 256 + lr] = sq;
;       SCHED();
;     }
.LBB0_156:
	s_or_b64 exec, exec, s[48:49]
	v_add_u32_e32 v30, 16, v36
	v_ashrrev_i32_e32 v31, 31, v30
	s_waitcnt lgkmcnt(0)
	v_lshlrev_b64 v[26:27], 13, v[30:31]
	v_lshl_add_u64 v[26:27], s[10:11], 0, v[26:27]
	v_lshl_add_u64 v[38:39], v[34:35], 2, v[26:27]
	s_waitcnt vmcnt(2)
	v_mov_b32_e32 v26, v240
	v_mov_b32_e32 v27, v241
	v_mov_b32_e32 v28, v242
	v_mov_b32_e32 v29, v243
	v_pk_fma_f32 v[26:27], v[20:21], 0.5, v[26:27] op_sel_hi:[1,0,1]
	v_pk_fma_f32 v[22:23], v[22:23], 0.5, v[28:29] op_sel_hi:[1,0,1]
	v_cvt_pk_bf16_f32 v20, v26, v27
	v_pk_mul_f32 v[40:41], v[26:27], v[26:27]
	v_cvt_pk_bf16_f32 v21, v22, v23
	v_pk_mul_f32 v[42:43], v[22:23], v[22:23]
	s_waitcnt vmcnt(1)
	v_mov_b32_e32 v26, v244
	v_mov_b32_e32 v27, v245
	v_mov_b32_e32 v28, v246
	v_mov_b32_e32 v29, v247
	v_pk_fma_f32 v[16:17], v[16:17], 0.5, v[26:27] op_sel_hi:[1,0,1]
	v_pk_fma_f32 v[18:19], v[18:19], 0.5, v[28:29] op_sel_hi:[1,0,1]
	v_cvt_pk_bf16_f32 v22, v16, v17
	v_pk_mul_f32 v[16:17], v[16:17], v[16:17]
	v_cvt_pk_bf16_f32 v23, v18, v19
	v_pk_mul_f32 v[18:19], v[18:19], v[18:19]
	v_add_f32_e32 v16, v16, v17
	v_add_f32_e32 v17, v40, v41
	v_add_f32_e32 v16, v18, v16
	v_add_f32_e32 v17, v42, v17
	v_add_f32_e32 v16, v19, v16
	v_add_f32_e32 v17, v43, v17
	v_add_f32_e32 v18, v17, v16
	v_add_u32_e32 v16, s1, v30
	v_ashrrev_i32_e32 v17, 31, v16
	v_lshlrev_b64 v[16:17], 12, v[16:17]
	v_lshl_add_u64 v[16:17], s[54:55], 0, v[16:17]
	v_permlane16_swap_b32_e32 v20, v22
	v_permlane16_swap_b32_e32 v21, v23
	v_lshl_add_u64 v[16:17], v[32:33], 1, v[16:17]
	global_store_dwordx4 v[16:17], v[20:23], off
	ds_bpermute_b32 v16, v135, v18
	s_waitcnt lgkmcnt(0)
	v_add_f32_e32 v16, v18, v16
	ds_bpermute_b32 v17, v134, v16
	s_and_saveexec_b64 s[48:49], s[8:9]
	s_cbranch_execz .LBB0_158
	s_waitcnt lgkmcnt(0)
	v_add_f32_e32 v16, v16, v17
	ds_write_b32 v24, v16 offset:4160
.LBB0_158:
	s_or_b64 exec, exec, s[48:49]
	v_add_u32_e32 v20, 32, v36
	v_ashrrev_i32_e32 v21, 31, v20
	s_waitcnt lgkmcnt(0)
	v_lshlrev_b64 v[16:17], 13, v[20:21]
	v_lshl_add_u64 v[16:17], s[10:11], 0, v[16:17]
	v_lshl_add_u64 v[22:23], v[34:35], 2, v[16:17]
	v_mov_b32_e32 v252, 0x20000
	v_mov_b32_e32 v253, 0
	global_load_dwordx4 v[232:235], v[22:23], off
	global_load_dwordx4 v[236:239], v[22:23], off offset:64
	v_lshl_add_u64 v[248:249], v[22:23], 0, v[252:253]
	global_load_dwordx4 v[240:243], v[248:249], off
	global_load_dwordx4 v[244:247], v[248:249], off offset:64
	s_waitcnt vmcnt(3)
	v_mov_b32_e32 v16, v232
	v_mov_b32_e32 v17, v233
	v_mov_b32_e32 v18, v234
	v_mov_b32_e32 v19, v235
	v_pk_fma_f32 v[16:17], v[12:13], 0.5, v[16:17] op_sel_hi:[1,0,1]
	v_pk_fma_f32 v[14:15], v[14:15], 0.5, v[18:19] op_sel_hi:[1,0,1]
	v_cvt_pk_bf16_f32 v12, v16, v17
	v_cvt_pk_bf16_f32 v13, v14, v15
	v_pk_mul_f32 v[18:19], v[16:17], v[16:17]
	v_pk_mul_f32 v[26:27], v[14:15], v[14:15]
	s_waitcnt vmcnt(2)
	v_mov_b32_e32 v14, v236
	v_mov_b32_e32 v15, v237
	v_mov_b32_e32 v16, v238
	v_mov_b32_e32 v17, v239
	v_pk_fma_f32 v[8:9], v[8:9], 0.5, v[14:15] op_sel_hi:[1,0,1]
	v_pk_fma_f32 v[10:11], v[10:11], 0.5, v[16:17] op_sel_hi:[1,0,1]
	v_cvt_pk_bf16_f32 v14, v8, v9
	v_pk_mul_f32 v[8:9], v[8:9], v[8:9]
	v_cvt_pk_bf16_f32 v15, v10, v11
	v_pk_mul_f32 v[10:11], v[10:11], v[10:11]
	v_add_f32_e32 v8, v8, v9
	v_add_f32_e32 v9, v18, v19
	v_add_f32_e32 v8, v10, v8
	v_add_f32_e32 v9, v26, v9
	v_add_f32_e32 v8, v11, v8
	v_add_f32_e32 v9, v27, v9
	v_add_f32_e32 v10, v9, v8
	v_add_u32_e32 v8, s1, v20
	v_ashrrev_i32_e32 v9, 31, v8
	v_lshlrev_b64 v[8:9], 12, v[8:9]
	v_lshl_add_u64 v[8:9], s[54:55], 0, v[8:9]
	v_permlane16_swap_b32_e32 v12, v14
	v_permlane16_swap_b32_e32 v13, v15
	v_lshl_add_u64 v[8:9], v[32:33], 1, v[8:9]
	global_store_dwordx4 v[8:9], v[12:15], off
	ds_bpermute_b32 v8, v135, v10
	s_waitcnt lgkmcnt(0)
	v_add_f32_e32 v8, v10, v8
	ds_bpermute_b32 v9, v134, v8
	s_and_saveexec_b64 s[48:49], s[8:9]
	s_cbranch_execz .LBB0_160
	s_waitcnt lgkmcnt(0)
	v_add_f32_e32 v8, v8, v9
	ds_write_b32 v24, v8 offset:4224
.LBB0_160:
	s_or_b64 exec, exec, s[48:49]
	v_add_u32_e32 v12, 48, v36
	v_ashrrev_i32_e32 v13, 31, v12
	s_waitcnt lgkmcnt(0)
	v_lshlrev_b64 v[8:9], 13, v[12:13]
	v_lshl_add_u64 v[8:9], s[10:11], 0, v[8:9]
	v_lshl_add_u64 v[14:15], v[34:35], 2, v[8:9]
	s_waitcnt vmcnt(2)
	v_mov_b32_e32 v8, v240
	v_mov_b32_e32 v9, v241
	v_mov_b32_e32 v10, v242
	v_mov_b32_e32 v11, v243
	v_pk_fma_f32 v[8:9], v[4:5], 0.5, v[8:9] op_sel_hi:[1,0,1]
	v_pk_fma_f32 v[6:7], v[6:7], 0.5, v[10:11] op_sel_hi:[1,0,1]
	v_cvt_pk_bf16_f32 v4, v8, v9
	v_cvt_pk_bf16_f32 v5, v6, v7
	v_pk_mul_f32 v[10:11], v[8:9], v[8:9]
	v_pk_mul_f32 v[16:17], v[6:7], v[6:7]
	s_waitcnt vmcnt(1)
	v_mov_b32_e32 v6, v244
	v_mov_b32_e32 v7, v245
	v_mov_b32_e32 v8, v246
	v_mov_b32_e32 v9, v247
	v_pk_fma_f32 v[0:1], v[0:1], 0.5, v[6:7] op_sel_hi:[1,0,1]
	v_pk_fma_f32 v[2:3], v[2:3], 0.5, v[8:9] op_sel_hi:[1,0,1]
	v_cvt_pk_bf16_f32 v6, v0, v1
	v_pk_mul_f32 v[0:1], v[0:1], v[0:1]
	v_cvt_pk_bf16_f32 v7, v2, v3
	v_pk_mul_f32 v[2:3], v[2:3], v[2:3]
	v_add_f32_e32 v0, v0, v1
	v_add_f32_e32 v1, v10, v11
	v_add_f32_e32 v0, v2, v0
	v_add_f32_e32 v1, v16, v1
	v_add_f32_e32 v0, v3, v0
	v_add_f32_e32 v1, v17, v1
	v_add_f32_e32 v2, v1, v0
	v_add_u32_e32 v0, s1, v12
	v_ashrrev_i32_e32 v1, 31, v0
	v_lshlrev_b64 v[0:1], 12, v[0:1]
	v_lshl_add_u64 v[0:1], s[54:55], 0, v[0:1]
	v_permlane16_swap_b32_e32 v4, v6
	v_permlane16_swap_b32_e32 v5, v7
	v_lshl_add_u64 v[0:1], v[32:33], 1, v[0:1]
	global_store_dwordx4 v[0:1], v[4:7], off
	ds_bpermute_b32 v0, v135, v2
	s_waitcnt lgkmcnt(0)
	v_add_f32_e32 v0, v2, v0
	ds_bpermute_b32 v1, v134, v0
	s_and_saveexec_b64 s[10:11], s[8:9]
	s_cbranch_execz .LBB0_162
	s_waitcnt lgkmcnt(0)
	v_add_f32_e32 v0, v0, v1
	ds_write_b32 v24, v0 offset:4288

; #define TILE_DECODE(tl, PM, PN) do { const int band_ = (tl) / (16 * nN), idx_ = (tl) % (16 * nN), x_ = idx_ & 7, j_ = idx_ >> 3; \
;     PM = band_ * 16 + (x_ >> 1) * 4 + (j_ & 3); PN = (j_ >> 2) * 2 + (x_ & 1); } while (0)
; template <int EPI>
; __device__ __forceinline__ void gemm_phase(char* shm, const u16* __restrict__ A, int lda, int a_pn_off,
;                                            const u16* __restrict__ Bt, int K, int nN, const EpiArgs& e) {
;     ...
;     const int ntile = tile + gridDim.x;
;     const bool has_next = ntile < ntiles;
;     if (has_next) TILE_DECODE(ntile, pm_n, pn_n);
.LBB0_181:
	s_lshl_b32 s28, s30, 8
	s_add_i32 s18, s18, s33
	s_cmpk_gt_i32 s18, 0x17ff
	s_cselect_b64 s[26:27], -1, 0
	s_cmpk_lt_i32 s18, 0x1800
	s_cselect_b64 s[70:71], -1, 0
	s_and_b64 vcc, exec, s[26:27]
	s_mov_b32 s31, s28
	s_mov_b32 s22, s8
	s_mov_b32 s20, s30
	s_cbranch_vccnz .LBB0_183
	s_ashr_i32 s9, s18, 31
	s_lshr_b32 s9, s9, 23
	s_add_i32 s9, s18, s9
	s_ashr_i32 s10, s9, 9
	s_and_b32 s9, s9, 0xfffffe00
	s_sub_i32 s9, s18, s9
	s_lshl_b32 s11, s9, 1
	s_lshl_b32 s10, s10, 4
	s_and_b32 s11, s11, 12
	s_or_b32 s10, s11, s10
	s_bfe_u32 s11, s9, 0x20003
	s_or_b32 s20, s10, s11
	s_lshr_b32 s11, s20, 4
	s_lshl_b32 s11, s11, 1
	s_ashr_i32 s10, s9, 4
	s_and_b32 s10, s10, -2
	s_add_i32 s11, s11, s10
	s_and_b32 s11, s11, 14
	s_and_b32 s10, s10, 16
	s_or_b32 s10, s10, s11
	s_and_b32 s9, s9, 1
	s_or_b32 s22, s10, s9
	s_lshl_b32 s31, s20, 8

; #define WAIT_V(n) asm volatile("s_waitcnt vmcnt(%0)" ::"n"(n) : "memory")
; #define BAR __builtin_amdgcn_s_barrier()
; template <int EPI, bool SWP> ...
;     ...
;   } else {
;     if (wr == 1) BAR;
;     WAIT_V(0); BAR;
;     BAR;
;   }
;   float ss_next = 0.f;
;   if (has_next && e.nss > 0 && tid < 256)
;     for (int i = 0; i < e.nss; ++i) ss_next += e.ss[(size_t)(brow_n + tid) * e.nss + i];
.LBB0_682:
	s_waitcnt vmcnt(8)
	s_barrier
	s_barrier
	s_nor_b64 s[92:93], s[6:7], s[48:49]
	v_mov_b32_e32 v235, 0x358637bd
	s_and_saveexec_b64 s[70:71], s[92:93]
	s_cbranch_execnz .LBB0_665
	s_branch .LBB0_666

; #define SCHED() __builtin_amdgcn_sched_barrier(0)
; template <int EPI, int MB, int NB> ...
;     ...
;   } else if constexpr (EPI == EPI_RES) {
;     const float* res = brow < e.res_split ? e.res0 + (size_t)brow * DM : e.res1 + (size_t)(brow - e.res_split) * DM;
;     const bool rb = e.resb != nullptr;
; #pragma unroll
;     for (int m = 0; m < MB; ++m) {
;       const int lr = lrow0 + m * 16;
;       float sq = 0.f;
;       u32x2 ob[2], rw[2];
;       if (rb) unwiden16(*(const i32x4*)(e.resb + (size_t)(brow + lr) * DM + colw), rw[0], rw[1]);
; #pragma unroll
;       for (int n = 0; n < NB; ++n) {
;         const int col = col0 + n * 16;
;         float4 r4;
;         if (rb) {
;           const u32x2 rr = rw[n];
;           r4.x = __uint_as_float(rr[0] << 16); r4.y = __uint_as_float(rr[0] & 0xffff0000u);
;           r4.z = __uint_as_float(rr[1] << 16); r4.w = __uint_as_float(rr[1] & 0xffff0000u);
;         } else {
;           r4 = *(const float4*)(res + (size_t)lr * DM + col);
;         }
;         float4 v;
;         v.x = r4.x + e.alpha * acc[m][n][0]; v.y = r4.y + e.alpha * acc[m][n][1];
;         v.z = r4.z + e.alpha * acc[m][n][2]; v.w = r4.w + e.alpha * acc[m][n][3];
;         ob[n][0] = pk_bf16(v.x, v.y); ob[n][1] = pk_bf16(v.z, v.w);
;         sq += v.x * v.x + v.y * v.y + v.z * v.z + v.w * v.w;
;       }
;       *(i32x4*)(e.o16 + (size_t)(brow + lr) * DM + colw) = widen16(ob[0], ob[1]);
;       sq += __shfl_xor(sq, 16); sq += __shfl_xor(sq, 32);
;       if (fq == 0) s_part[part_slot * 256 + lr] = sq;
;       SCHED();
;     }
.LBB0_716:
	v_mov_b32_e32 v144, v209
	v_mov_b32_e32 v128, v210
	v_add_u32_e32 v133, s90, v211
	v_add_u32_e32 v130, s11, v144
	v_add_u32_e32 v128, v128, v133
	v_ashrrev_i32_e32 v131, 31, v130
	v_ashrrev_i32_e32 v129, 31, v128
	v_lshlrev_b64 v[138:139], 12, v[130:131]
	v_lshl_add_u64 v[134:135], s[24:25], 0, v[138:139]
	v_lshlrev_b64 v[128:129], 1, v[128:129]
	v_lshl_add_u64 v[134:135], v[134:135], 0, v[128:129]
	v_mov_b32_e32 v252, 0x10000
	v_mov_b32_e32 v253, 0
	global_load_dwordx4 v[232:235], v[134:135], off
	v_lshl_add_u64 v[248:249], v[134:135], 0, v[252:253]
	global_load_dwordx4 v[236:239], v[248:249], off
	v_lshl_add_u64 v[248:249], v[248:249], 0, v[252:253]
	global_load_dwordx4 v[240:243], v[248:249], off
	v_lshl_add_u64 v[248:249], v[248:249], 0, v[252:253]
	global_load_dwordx4 v[244:247], v[248:249], off
	v_and_b32_e32 v132, 64, v215
	v_xor_b32_e32 v131, 16, v215
	v_add_u32_e32 v132, 64, v132
	v_xor_b32_e32 v140, 32, v215
	v_cmp_lt_i32_e32 vcc, v131, v132
	s_waitcnt vmcnt(3)
	v_mov_b32_e32 v134, v232
	v_mov_b32_e32 v135, v233
	v_mov_b32_e32 v136, v234
	v_mov_b32_e32 v137, v235
	v_mov_b32_e32 v141, v136
	v_cndmask_b32_e32 v131, v215, v131, vcc
	v_cmp_lt_i32_e32 vcc, v140, v132
	v_mov_b32_e32 v143, v137
	v_permlane16_swap_b32_e32 v134, v141
	v_cndmask_b32_e32 v140, v215, v140, vcc
	v_permlane16_swap_b32_e32 v135, v143
	v_lshlrev_b32_e32 v132, 2, v131
	v_lshlrev_b32_e32 v131, 2, v140
	v_lshlrev_b32_e32 v136, 16, v134
	v_and_b32_e32 v137, 0xffff0000, v134
	v_lshlrev_b32_e32 v134, 16, v135
	v_and_b32_e32 v135, 0xffff0000, v135
	v_lshlrev_b32_e32 v140, 16, v141
	v_and_b32_e32 v141, 0xffff0000, v141
	v_lshlrev_b32_e32 v142, 16, v143
	v_and_b32_e32 v143, 0xffff0000, v143
	v_pk_fma_f32 v[136:137], v[124:125], 0.5, v[136:137] op_sel_hi:[1,0,1]
	v_pk_fma_f32 v[126:127], v[126:127], 0.5, v[134:135] op_sel_hi:[1,0,1]
	v_pk_fma_f32 v[120:121], v[120:121], 0.5, v[140:141] op_sel_hi:[1,0,1]
	v_pk_fma_f32 v[122:123], v[122:123], 0.5, v[142:143] op_sel_hi:[1,0,1]
	v_cvt_pk_bf16_f32 v124, v136, v137
	v_cvt_pk_bf16_f32 v125, v126, v127
	v_pk_mul_f32 v[134:135], v[136:137], v[136:137]
	v_pk_mul_f32 v[136:137], v[126:127], v[126:127]
	v_cvt_pk_bf16_f32 v126, v120, v121
	v_pk_mul_f32 v[120:121], v[120:121], v[120:121]
	v_cvt_pk_bf16_f32 v127, v122, v123
	v_pk_mul_f32 v[122:123], v[122:123], v[122:123]
	v_add_f32_e32 v120, v121, v120
	v_add_f32_e32 v121, v135, v134
	v_add_f32_e32 v120, v122, v120
	v_add_f32_e32 v121, v136, v121
	v_add_f32_e32 v120, v123, v120
	v_add_f32_e32 v121, v137, v121
	v_add_f32_e32 v120, v121, v120
	ds_bpermute_b32 v121, v132, v120
	v_lshl_add_u64 v[134:135], s[0:1], 0, v[138:139]
	v_permlane16_swap_b32_e32 v124, v126
	v_permlane16_swap_b32_e32 v125, v127
	s_waitcnt lgkmcnt(0)
	v_add_f32_e32 v121, v120, v121
	ds_bpermute_b32 v122, v131, v121
	v_lshl_add_u64 v[134:135], v[134:135], 0, v[128:129]
	v_lshl_add_u32 v120, v144, 2, s72
	global_store_dwordx4 v[134:135], v[124:127], off
	s_and_saveexec_b64 s[66:67], s[6:7]
	s_cbranch_execz .LBB0_718
	s_waitcnt lgkmcnt(0)
	v_add_f32_e32 v121, v121, v122
	ds_write_b32 v120, v121
.LBB0_718:
	s_or_b64 exec, exec, s[66:67]
	s_waitcnt lgkmcnt(0)
	v_add_u32_e32 v122, 16, v130
	v_ashrrev_i32_e32 v123, 31, v122
	v_lshlrev_b64 v[126:127], 12, v[122:123]
	v_lshl_add_u64 v[122:123], s[24:25], 0, v[126:127]
	v_lshl_add_u64 v[122:123], v[122:123], 0, v[128:129]
	s_waitcnt vmcnt(3)
	v_mov_b32_e32 v122, v236
	v_mov_b32_e32 v123, v237
	v_mov_b32_e32 v124, v238
	v_mov_b32_e32 v125, v239
	v_mov_b32_e32 v121, v124
	v_mov_b32_e32 v137, v125
	s_nop 0
	v_permlane16_swap_b32_e32 v122, v121
	v_permlane16_swap_b32_e32 v123, v137
	v_lshlrev_b32_e32 v124, 16, v122
	v_and_b32_e32 v125, 0xffff0000, v122
	v_lshlrev_b32_e32 v134, 16, v121
	v_and_b32_e32 v135, 0xffff0000, v121
	v_lshlrev_b32_e32 v122, 16, v123
	v_and_b32_e32 v123, 0xffff0000, v123
	v_lshlrev_b32_e32 v136, 16, v137
	v_and_b32_e32 v137, 0xffff0000, v137
	v_pk_fma_f32 v[116:117], v[116:117], 0.5, v[124:125] op_sel_hi:[1,0,1]
	v_pk_fma_f32 v[112:113], v[112:113], 0.5, v[134:135] op_sel_hi:[1,0,1]
	v_pk_fma_f32 v[118:119], v[118:119], 0.5, v[122:123] op_sel_hi:[1,0,1]
	v_pk_fma_f32 v[122:123], v[114:115], 0.5, v[136:137] op_sel_hi:[1,0,1]
	v_cvt_pk_bf16_f32 v114, v116, v117
	v_pk_mul_f32 v[116:117], v[116:117], v[116:117]
	v_pk_mul_f32 v[124:125], v[112:113], v[112:113]
	v_cvt_pk_bf16_f32 v115, v118, v119
	v_pk_mul_f32 v[118:119], v[118:119], v[118:119]
	v_pk_mul_f32 v[134:135], v[122:123], v[122:123]
	v_add_f32_e32 v121, v125, v124
	v_add_f32_e32 v116, v117, v116
	v_add_f32_e32 v117, v134, v121
	v_add_f32_e32 v116, v118, v116
	v_add_f32_e32 v117, v135, v117
	v_add_f32_e32 v116, v119, v116
	v_add_f32_e32 v118, v116, v117
	ds_bpermute_b32 v119, v132, v118
	v_cvt_pk_bf16_f32 v116, v112, v113
	v_cvt_pk_bf16_f32 v117, v122, v123
	s_nop 0
	v_permlane16_swap_b32_e32 v114, v116
	s_waitcnt lgkmcnt(0)
	v_add_f32_e32 v112, v118, v119
	ds_bpermute_b32 v113, v131, v112
	v_lshl_add_u64 v[118:119], s[0:1], 0, v[126:127]
	v_permlane16_swap_b32_e32 v115, v117
	v_lshl_add_u64 v[118:119], v[118:119], 0, v[128:129]
	global_store_dwordx4 v[118:119], v[114:117], off
	s_and_saveexec_b64 s[66:67], s[6:7]
	s_cbranch_execz .LBB0_720
	s_waitcnt lgkmcnt(0)
	v_add_f32_e32 v112, v112, v113
	ds_write_b32 v120, v112 offset:64
; #define SCHED() __builtin_amdgcn_sched_barrier(0)
; template <int EPI, int MB, int NB> ...
;     ...
;   } else if constexpr (EPI == EPI_RES) {
;     const float* res = brow < e.res_split ? e.res0 + (size_t)brow * DM : e.res1 + (size_t)(brow - e.res_split) * DM;
;     const bool rb = e.resb != nullptr;
; #pragma unroll
;     for (int m = 0; m < MB; ++m) {
;       const int lr = lrow0 + m * 16;
;       float sq = 0.f;
;       u32x2 ob[2], rw[2];
;       if (rb) unwiden16(*(const i32x4*)(e.resb + (size_t)(brow + lr) * DM + colw), rw[0], rw[1]);
; #pragma unroll
;       for (int n = 0; n < NB; ++n) {
;         const int col = col0 + n * 16;
;         float4 r4;
;         if (rb) {
;           const u32x2 rr = rw[n];
;           r4.x = __uint_as_float(rr[0] << 16); r4.y = __uint_as_float(rr[0] & 0xffff0000u);
;           r4.z = __uint_as_float(rr[1] << 16); r4.w = __uint_as_float(rr[1] & 0xffff0000u);
;         } else {
;           r4 = *(const float4*)(res + (size_t)lr * DM + col);
;         }
;         float4 v;
;         v.x = r4.x + e.alpha * acc[m][n][0]; v.y = r4.y + e.alpha * acc[m][n][1];
;         v.z = r4.z + e.alpha * acc[m][n][2]; v.w = r4.w + e.alpha * acc[m][n][3];
;         ob[n][0] = pk_bf16(v.x, v.y); ob[n][1] = pk_bf16(v.z, v.w);
;         sq += v.x * v.x + v.y * v.y + v.z * v.z + v.w * v.w;
;       }
;       *(i32x4*)(e.o16 + (size_t)(brow + lr) * DM + colw) = widen16(ob[0], ob[1]);
;       sq += __shfl_xor(sq, 16); sq += __shfl_xor(sq, 32);
;       if (fq == 0) s_part[part_slot * 256 + lr] = sq;
;       SCHED();
;     }
.LBB0_720:
	s_or_b64 exec, exec, s[66:67]
	v_add_u32_e32 v112, 32, v130
	s_waitcnt lgkmcnt(0)
	v_ashrrev_i32_e32 v113, 31, v112
	v_lshlrev_b64 v[116:117], 12, v[112:113]
	v_lshl_add_u64 v[112:113], s[24:25], 0, v[116:117]
	v_lshl_add_u64 v[112:113], v[112:113], 0, v[128:129]
	s_waitcnt vmcnt(3)
	v_mov_b32_e32 v112, v240
	v_mov_b32_e32 v113, v241
	v_mov_b32_e32 v114, v242
	v_mov_b32_e32 v115, v243
	v_mov_b32_e32 v119, v114
	v_mov_b32_e32 v121, v115
	s_nop 0
	v_permlane16_swap_b32_e32 v112, v119
	v_permlane16_swap_b32_e32 v113, v121
	v_lshlrev_b32_e32 v114, 16, v112
	v_and_b32_e32 v115, 0xffff0000, v112
	v_lshlrev_b32_e32 v118, 16, v119
	v_and_b32_e32 v119, 0xffff0000, v119
	v_lshlrev_b32_e32 v112, 16, v113
	v_and_b32_e32 v113, 0xffff0000, v113
	v_lshlrev_b32_e32 v122, 16, v121
	v_and_b32_e32 v123, 0xffff0000, v121
	v_pk_fma_f32 v[108:109], v[108:109], 0.5, v[114:115] op_sel_hi:[1,0,1]
	v_pk_fma_f32 v[104:105], v[104:105], 0.5, v[118:119] op_sel_hi:[1,0,1]
	v_pk_fma_f32 v[110:111], v[110:111], 0.5, v[112:113] op_sel_hi:[1,0,1]
	v_pk_fma_f32 v[112:113], v[106:107], 0.5, v[122:123] op_sel_hi:[1,0,1]
	v_cvt_pk_bf16_f32 v106, v108, v109
	v_pk_mul_f32 v[108:109], v[108:109], v[108:109]
	v_pk_mul_f32 v[114:115], v[104:105], v[104:105]
	v_cvt_pk_bf16_f32 v107, v110, v111
	v_pk_mul_f32 v[110:111], v[110:111], v[110:111]
	v_pk_mul_f32 v[118:119], v[112:113], v[112:113]
	v_add_f32_e32 v114, v115, v114
	v_add_f32_e32 v108, v109, v108
	v_add_f32_e32 v109, v118, v114
	v_add_f32_e32 v108, v110, v108
	v_add_f32_e32 v109, v119, v109
	v_add_f32_e32 v108, v111, v108
	v_add_f32_e32 v110, v108, v109
	ds_bpermute_b32 v111, v132, v110
	v_cvt_pk_bf16_f32 v108, v104, v105
	v_cvt_pk_bf16_f32 v109, v112, v113
	s_nop 0
	v_permlane16_swap_b32_e32 v106, v108
	s_waitcnt lgkmcnt(0)
	v_add_f32_e32 v104, v110, v111
	ds_bpermute_b32 v105, v131, v104
	v_lshl_add_u64 v[110:111], s[0:1], 0, v[116:117]
	v_permlane16_swap_b32_e32 v107, v109
	v_lshl_add_u64 v[110:111], v[110:111], 0, v[128:129]
	global_store_dwordx4 v[110:111], v[106:109], off
	s_and_saveexec_b64 s[66:67], s[6:7]
	s_cbranch_execz .LBB0_722
	s_waitcnt lgkmcnt(0)
	v_add_f32_e32 v104, v104, v105
	ds_write_b32 v120, v104 offset:128
.LBB0_722:
	s_or_b64 exec, exec, s[66:67]
	v_add_u32_e32 v104, 48, v130
	s_waitcnt lgkmcnt(0)
	v_ashrrev_i32_e32 v105, 31, v104
	v_lshlrev_b64 v[108:109], 12, v[104:105]
	v_lshl_add_u64 v[104:105], s[24:25], 0, v[108:109]
	v_lshl_add_u64 v[104:105], v[104:105], 0, v[128:129]
	s_waitcnt vmcnt(3)
	v_mov_b32_e32 v104, v244
	v_mov_b32_e32 v105, v245
	v_mov_b32_e32 v106, v246
	v_mov_b32_e32 v107, v247
	v_mov_b32_e32 v111, v106
	v_mov_b32_e32 v113, v107
	s_nop 0
	v_permlane16_swap_b32_e32 v104, v111
	v_permlane16_swap_b32_e32 v105, v113
	v_lshlrev_b32_e32 v106, 16, v104
	v_and_b32_e32 v107, 0xffff0000, v104
	v_lshlrev_b32_e32 v110, 16, v111
	v_and_b32_e32 v111, 0xffff0000, v111
	v_lshlrev_b32_e32 v104, 16, v105
	v_and_b32_e32 v105, 0xffff0000, v105
	v_lshlrev_b32_e32 v112, 16, v113
	v_and_b32_e32 v113, 0xffff0000, v113
	v_pk_fma_f32 v[100:101], v[100:101], 0.5, v[106:107] op_sel_hi:[1,0,1]
	v_pk_fma_f32 v[96:97], v[96:97], 0.5, v[110:111] op_sel_hi:[1,0,1]
	v_pk_fma_f32 v[102:103], v[102:103], 0.5, v[104:105] op_sel_hi:[1,0,1]
	v_pk_fma_f32 v[104:105], v[98:99], 0.5, v[112:113] op_sel_hi:[1,0,1]
	v_cvt_pk_bf16_f32 v98, v100, v101
	v_pk_mul_f32 v[100:101], v[100:101], v[100:101]
	v_pk_mul_f32 v[106:107], v[96:97], v[96:97]
	v_cvt_pk_bf16_f32 v99, v102, v103
	v_pk_mul_f32 v[102:103], v[102:103], v[102:103]
	v_pk_mul_f32 v[110:111], v[104:105], v[104:105]
	v_add_f32_e32 v106, v107, v106
	v_add_f32_e32 v100, v101, v100
	v_add_f32_e32 v101, v110, v106
	v_add_f32_e32 v100, v102, v100
	v_add_f32_e32 v101, v111, v101
	v_add_f32_e32 v100, v103, v100
	v_add_f32_e32 v102, v100, v101
	ds_bpermute_b32 v103, v132, v102
	v_cvt_pk_bf16_f32 v100, v96, v97
	v_cvt_pk_bf16_f32 v101, v104, v105
	s_nop 0
	v_permlane16_swap_b32_e32 v98, v100
	s_waitcnt lgkmcnt(0)
	v_add_f32_e32 v96, v102, v103
	ds_bpermute_b32 v97, v131, v96
	v_lshl_add_u64 v[102:103], s[0:1], 0, v[108:109]
	v_permlane16_swap_b32_e32 v99, v101
	v_lshl_add_u64 v[102:103], v[102:103], 0, v[128:129]
	global_store_dwordx4 v[102:103], v[98:101], off
	s_and_saveexec_b64 s[66:67], s[6:7]
	s_cbranch_execz .LBB0_724
	s_waitcnt lgkmcnt(0)
	v_add_f32_e32 v96, v96, v97
	ds_write_b32 v120, v96 offset:192
; #define SCHED() __builtin_amdgcn_sched_barrier(0)
; template <int EPI, int MB, int NB> ...
;     ...
;   } else if constexpr (EPI == EPI_RES) {
;     const float* res = brow < e.res_split ? e.res0 + (size_t)brow * DM : e.res1 + (size_t)(brow - e.res_split) * DM;
;     const bool rb = e.resb != nullptr;
; #pragma unroll
;     for (int m = 0; m < MB; ++m) {
;       const int lr = lrow0 + m * 16;
;       float sq = 0.f;
;       u32x2 ob[2], rw[2];
;       if (rb) unwiden16(*(const i32x4*)(e.resb + (size_t)(brow + lr) * DM + colw), rw[0], rw[1]);
; #pragma unroll
;       for (int n = 0; n < NB; ++n) {
;         const int col = col0 + n * 16;
;         float4 r4;
;         if (rb) {
;           const u32x2 rr = rw[n];
;           r4.x = __uint_as_float(rr[0] << 16); r4.y = __uint_as_float(rr[0] & 0xffff0000u);
;           r4.z = __uint_as_float(rr[1] << 16); r4.w = __uint_as_float(rr[1] & 0xffff0000u);
;         } else {
;           r4 = *(const float4*)(res + (size_t)lr * DM + col);
;         }
;         float4 v;
;         v.x = r4.x + e.alpha * acc[m][n][0]; v.y = r4.y + e.alpha * acc[m][n][1];
;         v.z = r4.z + e.alpha * acc[m][n][2]; v.w = r4.w + e.alpha * acc[m][n][3];
;         ob[n][0] = pk_bf16(v.x, v.y); ob[n][1] = pk_bf16(v.z, v.w);
;         sq += v.x * v.x + v.y * v.y + v.z * v.z + v.w * v.w;
;       }
;       *(i32x4*)(e.o16 + (size_t)(brow + lr) * DM + colw) = widen16(ob[0], ob[1]);
;       sq += __shfl_xor(sq, 16); sq += __shfl_xor(sq, 32);
;       if (fq == 0) s_part[part_slot * 256 + lr] = sq;
;       SCHED();
;     }
.LBB0_724:
	s_or_b64 exec, exec, s[66:67]
	v_mov_b32_e32 v96, v212
	v_mov_b32_e32 v110, v209
	s_nop 0
	v_add_u32_e32 v98, s11, v110
	v_add_u32_e32 v96, v96, v133
	v_ashrrev_i32_e32 v99, 31, v98
	s_waitcnt lgkmcnt(0)
	v_ashrrev_i32_e32 v97, 31, v96
	v_lshlrev_b64 v[104:105], 12, v[98:99]
	v_lshl_add_u64 v[100:101], s[24:25], 0, v[104:105]
	v_lshlrev_b64 v[96:97], 1, v[96:97]
	v_lshl_add_u64 v[100:101], v[100:101], 0, v[96:97]
	v_mov_b32_e32 v252, 0x10000
	v_mov_b32_e32 v253, 0
	global_load_dwordx4 v[232:235], v[100:101], off
	v_lshl_add_u64 v[248:249], v[100:101], 0, v[252:253]
	global_load_dwordx4 v[236:239], v[248:249], off
	v_lshl_add_u64 v[248:249], v[248:249], 0, v[252:253]
	global_load_dwordx4 v[240:243], v[248:249], off
	v_lshl_add_u64 v[248:249], v[248:249], 0, v[252:253]
	global_load_dwordx4 v[244:247], v[248:249], off
	s_waitcnt vmcnt(3)
	v_mov_b32_e32 v100, v232
	v_mov_b32_e32 v101, v233
	v_mov_b32_e32 v102, v234
	v_mov_b32_e32 v103, v235
	v_mov_b32_e32 v99, v102
	v_mov_b32_e32 v109, v103
	s_nop 0
	v_permlane16_swap_b32_e32 v100, v99
	v_permlane16_swap_b32_e32 v101, v109
	v_lshlrev_b32_e32 v102, 16, v100
	v_and_b32_e32 v103, 0xffff0000, v100
	v_lshlrev_b32_e32 v100, 16, v101
	v_and_b32_e32 v101, 0xffff0000, v101
	v_lshlrev_b32_e32 v106, 16, v99
	v_and_b32_e32 v107, 0xffff0000, v99
	v_lshlrev_b32_e32 v108, 16, v109
	v_and_b32_e32 v109, 0xffff0000, v109
	v_pk_fma_f32 v[102:103], v[92:93], 0.5, v[102:103] op_sel_hi:[1,0,1]
	v_pk_fma_f32 v[94:95], v[94:95], 0.5, v[100:101] op_sel_hi:[1,0,1]
	v_pk_fma_f32 v[88:89], v[88:89], 0.5, v[106:107] op_sel_hi:[1,0,1]
	v_pk_fma_f32 v[90:91], v[90:91], 0.5, v[108:109] op_sel_hi:[1,0,1]
	v_cvt_pk_bf16_f32 v92, v102, v103
	v_cvt_pk_bf16_f32 v93, v94, v95
	v_pk_mul_f32 v[100:101], v[102:103], v[102:103]
	v_pk_mul_f32 v[102:103], v[94:95], v[94:95]
	v_cvt_pk_bf16_f32 v94, v88, v89
	v_pk_mul_f32 v[88:89], v[88:89], v[88:89]
	v_cvt_pk_bf16_f32 v95, v90, v91
	v_pk_mul_f32 v[90:91], v[90:91], v[90:91]
	v_add_f32_e32 v88, v89, v88
	v_add_f32_e32 v89, v101, v100
	v_add_f32_e32 v88, v90, v88
	v_add_f32_e32 v89, v102, v89
	v_add_f32_e32 v88, v91, v88
	v_add_f32_e32 v89, v103, v89
	v_add_f32_e32 v88, v89, v88
	ds_bpermute_b32 v89, v132, v88
	v_lshl_add_u64 v[100:101], s[0:1], 0, v[104:105]
	v_permlane16_swap_b32_e32 v92, v94
	v_permlane16_swap_b32_e32 v93, v95
	s_waitcnt lgkmcnt(0)
	v_add_f32_e32 v89, v88, v89
	ds_bpermute_b32 v90, v131, v89
	v_lshl_add_u64 v[100:101], v[100:101], 0, v[96:97]
	v_lshl_add_u32 v88, v110, 2, s72
	global_store_dwordx4 v[100:101], v[92:95], off
	s_and_saveexec_b64 s[66:67], s[6:7]
	s_cbranch_execz .LBB0_726
	s_waitcnt lgkmcnt(0)
	v_add_f32_e32 v89, v89, v90
	ds_write_b32 v88, v89 offset:4096
.LBB0_726:
	s_or_b64 exec, exec, s[66:67]
	s_waitcnt lgkmcnt(0)
	v_add_u32_e32 v90, 16, v98
	v_ashrrev_i32_e32 v91, 31, v90
	v_lshlrev_b64 v[94:95], 12, v[90:91]
	v_lshl_add_u64 v[90:91], s[24:25], 0, v[94:95]
	v_lshl_add_u64 v[90:91], v[90:91], 0, v[96:97]
	s_waitcnt vmcnt(3)
	v_mov_b32_e32 v90, v236
	v_mov_b32_e32 v91, v237
	v_mov_b32_e32 v92, v238
	v_mov_b32_e32 v93, v239
	v_mov_b32_e32 v89, v92
	v_mov_b32_e32 v99, v93
	s_nop 0
	v_permlane16_swap_b32_e32 v90, v89
	v_permlane16_swap_b32_e32 v91, v99
	v_lshlrev_b32_e32 v92, 16, v90
	v_and_b32_e32 v93, 0xffff0000, v90
	v_lshlrev_b32_e32 v100, 16, v89
	v_and_b32_e32 v101, 0xffff0000, v89
	v_lshlrev_b32_e32 v90, 16, v91
	v_and_b32_e32 v91, 0xffff0000, v91
	v_lshlrev_b32_e32 v102, 16, v99
	v_and_b32_e32 v103, 0xffff0000, v99
	v_pk_fma_f32 v[84:85], v[84:85], 0.5, v[92:93] op_sel_hi:[1,0,1]
	v_pk_fma_f32 v[80:81], v[80:81], 0.5, v[100:101] op_sel_hi:[1,0,1]
	v_pk_fma_f32 v[86:87], v[86:87], 0.5, v[90:91] op_sel_hi:[1,0,1]
	v_pk_fma_f32 v[90:91], v[82:83], 0.5, v[102:103] op_sel_hi:[1,0,1]
	v_cvt_pk_bf16_f32 v82, v84, v85
	v_pk_mul_f32 v[84:85], v[84:85], v[84:85]
	v_pk_mul_f32 v[92:93], v[80:81], v[80:81]
	v_cvt_pk_bf16_f32 v83, v86, v87
	v_pk_mul_f32 v[86:87], v[86:87], v[86:87]
	v_pk_mul_f32 v[100:101], v[90:91], v[90:91]
	v_add_f32_e32 v89, v93, v92
	v_add_f32_e32 v84, v85, v84
	v_add_f32_e32 v85, v100, v89
	v_add_f32_e32 v84, v86, v84
	v_add_f32_e32 v85, v101, v85
	v_add_f32_e32 v84, v87, v84
	v_add_f32_e32 v86, v84, v85
	ds_bpermute_b32 v87, v132, v86
	v_cvt_pk_bf16_f32 v84, v80, v81
	v_cvt_pk_bf16_f32 v85, v90, v91
	s_nop 0
	v_permlane16_swap_b32_e32 v82, v84
	s_waitcnt lgkmcnt(0)
	v_add_f32_e32 v80, v86, v87
	ds_bpermute_b32 v81, v131, v80
	v_lshl_add_u64 v[86:87], s[0:1], 0, v[94:95]
	v_permlane16_swap_b32_e32 v83, v85
	v_lshl_add_u64 v[86:87], v[86:87], 0, v[96:97]
	global_store_dwordx4 v[86:87], v[82:85], off
	s_and_saveexec_b64 s[66:67], s[6:7]
	s_cbranch_execz .LBB0_728
	s_waitcnt lgkmcnt(0)
	v_add_f32_e32 v80, v80, v81
	ds_write_b32 v88, v80 offset:4160
; #define SCHED() __builtin_amdgcn_sched_barrier(0)
; template <int EPI, int MB, int NB> ...
;     ...
;   } else if constexpr (EPI == EPI_RES) {
;     const float* res = brow < e.res_split ? e.res0 + (size_t)brow * DM : e.res1 + (size_t)(brow - e.res_split) * DM;
;     const bool rb = e.resb != nullptr;
; #pragma unroll
;     for (int m = 0; m < MB; ++m) {
;       const int lr = lrow0 + m * 16;
;       float sq = 0.f;
;       u32x2 ob[2], rw[2];
;       if (rb) unwiden16(*(const i32x4*)(e.resb + (size_t)(brow + lr) * DM + colw), rw[0], rw[1]);
; #pragma unroll
;       for (int n = 0; n < NB; ++n) {
;         const int col = col0 + n * 16;
;         float4 r4;
;         if (rb) {
;           const u32x2 rr = rw[n];
;           r4.x = __uint_as_float(rr[0] << 16); r4.y = __uint_as_float(rr[0] & 0xffff0000u);
;           r4.z = __uint_as_float(rr[1] << 16); r4.w = __uint_as_float(rr[1] & 0xffff0000u);
;         } else {
;           r4 = *(const float4*)(res + (size_t)lr * DM + col);
;         }
;         float4 v;
;         v.x = r4.x + e.alpha * acc[m][n][0]; v.y = r4.y + e.alpha * acc[m][n][1];
;         v.z = r4.z + e.alpha * acc[m][n][2]; v.w = r4.w + e.alpha * acc[m][n][3];
;         ob[n][0] = pk_bf16(v.x, v.y); ob[n][1] = pk_bf16(v.z, v.w);
;         sq += v.x * v.x + v.y * v.y + v.z * v.z + v.w * v.w;
;       }
;       *(i32x4*)(e.o16 + (size_t)(brow + lr) * DM + colw) = widen16(ob[0], ob[1]);
;       sq += __shfl_xor(sq, 16); sq += __shfl_xor(sq, 32);
;       if (fq == 0) s_part[part_slot * 256 + lr] = sq;
;       SCHED();
;     }
.LBB0_728:
	s_or_b64 exec, exec, s[66:67]
	v_add_u32_e32 v80, 32, v98
	s_waitcnt lgkmcnt(0)
	v_ashrrev_i32_e32 v81, 31, v80
	v_lshlrev_b64 v[84:85], 12, v[80:81]
	v_lshl_add_u64 v[80:81], s[24:25], 0, v[84:85]
	v_lshl_add_u64 v[80:81], v[80:81], 0, v[96:97]
	s_waitcnt vmcnt(3)
	v_mov_b32_e32 v80, v240
	v_mov_b32_e32 v81, v241
	v_mov_b32_e32 v82, v242
	v_mov_b32_e32 v83, v243
	v_mov_b32_e32 v87, v82
	v_mov_b32_e32 v89, v83
	s_nop 0
	v_permlane16_swap_b32_e32 v80, v87
	v_permlane16_swap_b32_e32 v81, v89
	v_lshlrev_b32_e32 v82, 16, v80
	v_and_b32_e32 v83, 0xffff0000, v80
	v_lshlrev_b32_e32 v86, 16, v87
	v_and_b32_e32 v87, 0xffff0000, v87
	v_lshlrev_b32_e32 v80, 16, v81
	v_and_b32_e32 v81, 0xffff0000, v81
	v_lshlrev_b32_e32 v90, 16, v89
	v_and_b32_e32 v91, 0xffff0000, v89
	v_pk_fma_f32 v[76:77], v[76:77], 0.5, v[82:83] op_sel_hi:[1,0,1]
	v_pk_fma_f32 v[72:73], v[72:73], 0.5, v[86:87] op_sel_hi:[1,0,1]
	v_pk_fma_f32 v[78:79], v[78:79], 0.5, v[80:81] op_sel_hi:[1,0,1]
	v_pk_fma_f32 v[80:81], v[74:75], 0.5, v[90:91] op_sel_hi:[1,0,1]
	v_cvt_pk_bf16_f32 v74, v76, v77
	v_pk_mul_f32 v[76:77], v[76:77], v[76:77]
	v_pk_mul_f32 v[82:83], v[72:73], v[72:73]
	v_cvt_pk_bf16_f32 v75, v78, v79
	v_pk_mul_f32 v[78:79], v[78:79], v[78:79]
	v_pk_mul_f32 v[86:87], v[80:81], v[80:81]
	v_add_f32_e32 v82, v83, v82
	v_add_f32_e32 v76, v77, v76
	v_add_f32_e32 v77, v86, v82
	v_add_f32_e32 v76, v78, v76
	v_add_f32_e32 v77, v87, v77
	v_add_f32_e32 v76, v79, v76
	v_add_f32_e32 v78, v76, v77
	ds_bpermute_b32 v79, v132, v78
	v_cvt_pk_bf16_f32 v76, v72, v73
	v_cvt_pk_bf16_f32 v77, v80, v81
	s_nop 0
	v_permlane16_swap_b32_e32 v74, v76
	s_waitcnt lgkmcnt(0)
	v_add_f32_e32 v72, v78, v79
	ds_bpermute_b32 v73, v131, v72
	v_lshl_add_u64 v[78:79], s[0:1], 0, v[84:85]
	v_permlane16_swap_b32_e32 v75, v77
	v_lshl_add_u64 v[78:79], v[78:79], 0, v[96:97]
	global_store_dwordx4 v[78:79], v[74:77], off
	s_and_saveexec_b64 s[66:67], s[6:7]
	s_cbranch_execz .LBB0_730
	s_waitcnt lgkmcnt(0)
	v_add_f32_e32 v72, v72, v73
	ds_write_b32 v88, v72 offset:4224
.LBB0_730:
	s_or_b64 exec, exec, s[66:67]
	v_add_u32_e32 v72, 48, v98
	s_waitcnt lgkmcnt(0)
	v_ashrrev_i32_e32 v73, 31, v72
	v_lshlrev_b64 v[76:77], 12, v[72:73]
	v_lshl_add_u64 v[72:73], s[24:25], 0, v[76:77]
	v_lshl_add_u64 v[72:73], v[72:73], 0, v[96:97]
	s_waitcnt vmcnt(3)
	v_mov_b32_e32 v72, v244
	v_mov_b32_e32 v73, v245
	v_mov_b32_e32 v74, v246
	v_mov_b32_e32 v75, v247
	v_mov_b32_e32 v79, v74
	v_mov_b32_e32 v81, v75
	s_nop 0
	v_permlane16_swap_b32_e32 v72, v79
	v_permlane16_swap_b32_e32 v73, v81
	v_lshlrev_b32_e32 v74, 16, v72
	v_and_b32_e32 v75, 0xffff0000, v72
	v_lshlrev_b32_e32 v78, 16, v79
	v_and_b32_e32 v79, 0xffff0000, v79
	v_lshlrev_b32_e32 v72, 16, v73
	v_and_b32_e32 v73, 0xffff0000, v73
	v_lshlrev_b32_e32 v80, 16, v81
	v_and_b32_e32 v81, 0xffff0000, v81
	v_pk_fma_f32 v[68:69], v[68:69], 0.5, v[74:75] op_sel_hi:[1,0,1]
	v_pk_fma_f32 v[64:65], v[64:65], 0.5, v[78:79] op_sel_hi:[1,0,1]
	v_pk_fma_f32 v[70:71], v[70:71], 0.5, v[72:73] op_sel_hi:[1,0,1]
	v_pk_fma_f32 v[72:73], v[66:67], 0.5, v[80:81] op_sel_hi:[1,0,1]
	v_cvt_pk_bf16_f32 v66, v68, v69
	v_pk_mul_f32 v[68:69], v[68:69], v[68:69]
	v_pk_mul_f32 v[74:75], v[64:65], v[64:65]
	v_cvt_pk_bf16_f32 v67, v70, v71
	v_pk_mul_f32 v[70:71], v[70:71], v[70:71]
	v_pk_mul_f32 v[78:79], v[72:73], v[72:73]
	v_add_f32_e32 v74, v75, v74
	v_add_f32_e32 v68, v69, v68
	v_add_f32_e32 v69, v78, v74
	v_add_f32_e32 v68, v70, v68
	v_add_f32_e32 v69, v79, v69
	v_add_f32_e32 v68, v71, v68
	v_add_f32_e32 v70, v68, v69
	ds_bpermute_b32 v71, v132, v70
	v_cvt_pk_bf16_f32 v68, v64, v65
	v_cvt_pk_bf16_f32 v69, v72, v73
	s_nop 0
	v_permlane16_swap_b32_e32 v66, v68
	s_waitcnt lgkmcnt(0)
	v_add_f32_e32 v64, v70, v71
	ds_bpermute_b32 v65, v131, v64
	v_lshl_add_u64 v[70:71], s[0:1], 0, v[76:77]
	v_permlane16_swap_b32_e32 v67, v69
	v_lshl_add_u64 v[70:71], v[70:71], 0, v[96:97]
	global_store_dwordx4 v[70:71], v[66:69], off
	s_and_saveexec_b64 s[66:67], s[6:7]
	s_cbranch_execz .LBB0_732
	s_waitcnt lgkmcnt(0)
	v_add_f32_e32 v64, v64, v65
	ds_write_b32 v88, v64 offset:4288
.LBB0_732:
	s_or_b64 exec, exec, s[66:67]
	v_mov_b32_e32 v78, v213
	v_mov_b32_e32 v64, v210
	s_nop 0
	v_add_u32_e32 v66, s11, v78
	v_add_u32_e32 v64, v64, v133
	v_ashrrev_i32_e32 v67, 31, v66
	s_waitcnt lgkmcnt(0)
	v_ashrrev_i32_e32 v65, 31, v64
	v_lshlrev_b64 v[72:73], 12, v[66:67]
	v_lshl_add_u64 v[68:69], s[24:25], 0, v[72:73]
	v_lshlrev_b64 v[64:65], 1, v[64:65]
	v_lshl_add_u64 v[68:69], v[68:69], 0, v[64:65]
	v_mov_b32_e32 v252, 0x10000
	v_mov_b32_e32 v253, 0
	global_load_dwordx4 v[232:235], v[68:69], off
	v_lshl_add_u64 v[248:249], v[68:69], 0, v[252:253]
	global_load_dwordx4 v[236:239], v[248:249], off
	v_lshl_add_u64 v[248:249], v[248:249], 0, v[252:253]
	global_load_dwordx4 v[240:243], v[248:249], off
	v_lshl_add_u64 v[248:249], v[248:249], 0, v[252:253]
	global_load_dwordx4 v[244:247], v[248:249], off
	s_waitcnt vmcnt(3)
	v_mov_b32_e32 v68, v232
	v_mov_b32_e32 v69, v233
	v_mov_b32_e32 v70, v234
	v_mov_b32_e32 v71, v235
	v_mov_b32_e32 v67, v70
	v_mov_b32_e32 v77, v71
	s_nop 0
	v_permlane16_swap_b32_e32 v68, v67
	v_permlane16_swap_b32_e32 v69, v77
	v_lshlrev_b32_e32 v70, 16, v68
	v_and_b32_e32 v71, 0xffff0000, v68
	v_lshlrev_b32_e32 v68, 16, v69
	v_and_b32_e32 v69, 0xffff0000, v69
	v_lshlrev_b32_e32 v74, 16, v67
	v_and_b32_e32 v75, 0xffff0000, v67
	v_lshlrev_b32_e32 v76, 16, v77
	v_and_b32_e32 v77, 0xffff0000, v77
	v_pk_fma_f32 v[70:71], v[60:61], 0.5, v[70:71] op_sel_hi:[1,0,1]
	v_pk_fma_f32 v[62:63], v[62:63], 0.5, v[68:69] op_sel_hi:[1,0,1]
	v_pk_fma_f32 v[56:57], v[56:57], 0.5, v[74:75] op_sel_hi:[1,0,1]
	v_pk_fma_f32 v[58:59], v[58:59], 0.5, v[76:77] op_sel_hi:[1,0,1]
	v_cvt_pk_bf16_f32 v60, v70, v71
	v_cvt_pk_bf16_f32 v61, v62, v63
	v_pk_mul_f32 v[68:69], v[70:71], v[70:71]
	v_pk_mul_f32 v[70:71], v[62:63], v[62:63]
	v_cvt_pk_bf16_f32 v62, v56, v57
	v_pk_mul_f32 v[56:57], v[56:57], v[56:57]
	v_cvt_pk_bf16_f32 v63, v58, v59
	v_pk_mul_f32 v[58:59], v[58:59], v[58:59]
	v_add_f32_e32 v56, v57, v56
	v_add_f32_e32 v57, v69, v68
	v_add_f32_e32 v56, v58, v56
	v_add_f32_e32 v57, v70, v57
	v_add_f32_e32 v56, v59, v56
	v_add_f32_e32 v57, v71, v57
	v_add_f32_e32 v56, v57, v56
	ds_bpermute_b32 v57, v132, v56
	v_lshl_add_u64 v[68:69], s[0:1], 0, v[72:73]
	v_permlane16_swap_b32_e32 v60, v62
	v_permlane16_swap_b32_e32 v61, v63
	s_waitcnt lgkmcnt(0)
	v_add_f32_e32 v57, v56, v57
	ds_bpermute_b32 v58, v131, v57
	v_lshl_add_u64 v[68:69], v[68:69], 0, v[64:65]
	v_lshl_add_u32 v56, v78, 2, s72
	global_store_dwordx4 v[68:69], v[60:63], off
	s_and_saveexec_b64 s[66:67], s[6:7]
	s_cbranch_execz .LBB0_734
	s_waitcnt lgkmcnt(0)
	v_add_f32_e32 v57, v57, v58
	ds_write_b32 v56, v57
; #define SCHED() __builtin_amdgcn_sched_barrier(0)
; template <int EPI, int MB, int NB> ...
;     ...
;   } else if constexpr (EPI == EPI_RES) {
;     const float* res = brow < e.res_split ? e.res0 + (size_t)brow * DM : e.res1 + (size_t)(brow - e.res_split) * DM;
;     const bool rb = e.resb != nullptr;
; #pragma unroll
;     for (int m = 0; m < MB; ++m) {
;       const int lr = lrow0 + m * 16;
;       float sq = 0.f;
;       u32x2 ob[2], rw[2];
;       if (rb) unwiden16(*(const i32x4*)(e.resb + (size_t)(brow + lr) * DM + colw), rw[0], rw[1]);
; #pragma unroll
;       for (int n = 0; n < NB; ++n) {
;         const int col = col0 + n * 16;
;         float4 r4;
;         if (rb) {
;           const u32x2 rr = rw[n];
;           r4.x = __uint_as_float(rr[0] << 16); r4.y = __uint_as_float(rr[0] & 0xffff0000u);
;           r4.z = __uint_as_float(rr[1] << 16); r4.w = __uint_as_float(rr[1] & 0xffff0000u);
;         } else {
;           r4 = *(const float4*)(res + (size_t)lr * DM + col);
;         }
;         float4 v;
;         v.x = r4.x + e.alpha * acc[m][n][0]; v.y = r4.y + e.alpha * acc[m][n][1];
;         v.z = r4.z + e.alpha * acc[m][n][2]; v.w = r4.w + e.alpha * acc[m][n][3];
;         ob[n][0] = pk_bf16(v.x, v.y); ob[n][1] = pk_bf16(v.z, v.w);
;         sq += v.x * v.x + v.y * v.y + v.z * v.z + v.w * v.w;
;       }
;       *(i32x4*)(e.o16 + (size_t)(brow + lr) * DM + colw) = widen16(ob[0], ob[1]);
;       sq += __shfl_xor(sq, 16); sq += __shfl_xor(sq, 32);
;       if (fq == 0) s_part[part_slot * 256 + lr] = sq;
;       SCHED();
;     }
.LBB0_734:
	s_or_b64 exec, exec, s[66:67]
	s_waitcnt lgkmcnt(0)
	v_add_u32_e32 v58, 16, v66
	v_ashrrev_i32_e32 v59, 31, v58
	v_lshlrev_b64 v[62:63], 12, v[58:59]
	v_lshl_add_u64 v[58:59], s[24:25], 0, v[62:63]
	v_lshl_add_u64 v[58:59], v[58:59], 0, v[64:65]
	s_waitcnt vmcnt(3)
	v_mov_b32_e32 v58, v236
	v_mov_b32_e32 v59, v237
	v_mov_b32_e32 v60, v238
	v_mov_b32_e32 v61, v239
	v_mov_b32_e32 v57, v60
	v_mov_b32_e32 v67, v61
	s_nop 0
	v_permlane16_swap_b32_e32 v58, v57
	v_permlane16_swap_b32_e32 v59, v67
	v_lshlrev_b32_e32 v60, 16, v58
	v_and_b32_e32 v61, 0xffff0000, v58
	v_lshlrev_b32_e32 v68, 16, v57
	v_and_b32_e32 v69, 0xffff0000, v57
	v_lshlrev_b32_e32 v58, 16, v59
	v_and_b32_e32 v59, 0xffff0000, v59
	v_lshlrev_b32_e32 v70, 16, v67
	v_and_b32_e32 v71, 0xffff0000, v67
	v_pk_fma_f32 v[52:53], v[52:53], 0.5, v[60:61] op_sel_hi:[1,0,1]
	v_pk_fma_f32 v[48:49], v[48:49], 0.5, v[68:69] op_sel_hi:[1,0,1]
	v_pk_fma_f32 v[54:55], v[54:55], 0.5, v[58:59] op_sel_hi:[1,0,1]
	v_pk_fma_f32 v[58:59], v[50:51], 0.5, v[70:71] op_sel_hi:[1,0,1]
	v_cvt_pk_bf16_f32 v50, v52, v53
	v_pk_mul_f32 v[52:53], v[52:53], v[52:53]
	v_pk_mul_f32 v[60:61], v[48:49], v[48:49]
	v_cvt_pk_bf16_f32 v51, v54, v55
	v_pk_mul_f32 v[54:55], v[54:55], v[54:55]
	v_pk_mul_f32 v[68:69], v[58:59], v[58:59]
	v_add_f32_e32 v57, v61, v60
	v_add_f32_e32 v52, v53, v52
	v_add_f32_e32 v53, v68, v57
	v_add_f32_e32 v52, v54, v52
	v_add_f32_e32 v53, v69, v53
	v_add_f32_e32 v52, v55, v52
	v_add_f32_e32 v54, v52, v53
	ds_bpermute_b32 v55, v132, v54
	v_cvt_pk_bf16_f32 v52, v48, v49
	v_cvt_pk_bf16_f32 v53, v58, v59
	s_nop 0
	v_permlane16_swap_b32_e32 v50, v52
	s_waitcnt lgkmcnt(0)
	v_add_f32_e32 v48, v54, v55
	ds_bpermute_b32 v49, v131, v48
	v_lshl_add_u64 v[54:55], s[0:1], 0, v[62:63]
	v_permlane16_swap_b32_e32 v51, v53
	v_lshl_add_u64 v[54:55], v[54:55], 0, v[64:65]
	global_store_dwordx4 v[54:55], v[50:53], off
	s_and_saveexec_b64 s[66:67], s[6:7]
	s_cbranch_execz .LBB0_736
	s_waitcnt lgkmcnt(0)
	v_add_f32_e32 v48, v48, v49
	ds_write_b32 v56, v48 offset:64
.LBB0_736:
	s_or_b64 exec, exec, s[66:67]
	v_add_u32_e32 v48, 32, v66
	s_waitcnt lgkmcnt(0)
	v_ashrrev_i32_e32 v49, 31, v48
	v_lshlrev_b64 v[52:53], 12, v[48:49]
	v_lshl_add_u64 v[48:49], s[24:25], 0, v[52:53]
	v_lshl_add_u64 v[48:49], v[48:49], 0, v[64:65]
	s_waitcnt vmcnt(3)
	v_mov_b32_e32 v48, v240
	v_mov_b32_e32 v49, v241
	v_mov_b32_e32 v50, v242
	v_mov_b32_e32 v51, v243
	v_mov_b32_e32 v55, v50
	v_mov_b32_e32 v57, v51
	s_nop 0
	v_permlane16_swap_b32_e32 v48, v55
	v_permlane16_swap_b32_e32 v49, v57
	v_lshlrev_b32_e32 v50, 16, v48
	v_and_b32_e32 v51, 0xffff0000, v48
	v_lshlrev_b32_e32 v54, 16, v55
	v_and_b32_e32 v55, 0xffff0000, v55
	v_lshlrev_b32_e32 v48, 16, v49
	v_and_b32_e32 v49, 0xffff0000, v49
	v_lshlrev_b32_e32 v58, 16, v57
	v_and_b32_e32 v59, 0xffff0000, v57
	v_pk_fma_f32 v[44:45], v[44:45], 0.5, v[50:51] op_sel_hi:[1,0,1]
	v_pk_fma_f32 v[40:41], v[40:41], 0.5, v[54:55] op_sel_hi:[1,0,1]
	v_pk_fma_f32 v[46:47], v[46:47], 0.5, v[48:49] op_sel_hi:[1,0,1]
	v_pk_fma_f32 v[48:49], v[42:43], 0.5, v[58:59] op_sel_hi:[1,0,1]
	v_cvt_pk_bf16_f32 v42, v44, v45
	v_pk_mul_f32 v[44:45], v[44:45], v[44:45]
	v_pk_mul_f32 v[50:51], v[40:41], v[40:41]
	v_cvt_pk_bf16_f32 v43, v46, v47
	v_pk_mul_f32 v[46:47], v[46:47], v[46:47]
	v_pk_mul_f32 v[54:55], v[48:49], v[48:49]
	v_add_f32_e32 v50, v51, v50
	v_add_f32_e32 v44, v45, v44
	v_add_f32_e32 v45, v54, v50
	v_add_f32_e32 v44, v46, v44
	v_add_f32_e32 v45, v55, v45
	v_add_f32_e32 v44, v47, v44
	v_add_f32_e32 v46, v44, v45
	ds_bpermute_b32 v47, v132, v46
	v_cvt_pk_bf16_f32 v44, v40, v41
	v_cvt_pk_bf16_f32 v45, v48, v49
	s_nop 0
	v_permlane16_swap_b32_e32 v42, v44
	s_waitcnt lgkmcnt(0)
	v_add_f32_e32 v40, v46, v47
	ds_bpermute_b32 v41, v131, v40
	v_lshl_add_u64 v[46:47], s[0:1], 0, v[52:53]
	v_permlane16_swap_b32_e32 v43, v45
	v_lshl_add_u64 v[46:47], v[46:47], 0, v[64:65]
	global_store_dwordx4 v[46:47], v[42:45], off
	s_and_saveexec_b64 s[66:67], s[6:7]
	s_cbranch_execz .LBB0_738
	s_waitcnt lgkmcnt(0)
	v_add_f32_e32 v40, v40, v41
	ds_write_b32 v56, v40 offset:128
.LBB0_738:
	s_or_b64 exec, exec, s[66:67]
	v_add_u32_e32 v40, 48, v66
	s_waitcnt lgkmcnt(0)
	v_ashrrev_i32_e32 v41, 31, v40
	v_lshlrev_b64 v[44:45], 12, v[40:41]
	v_lshl_add_u64 v[40:41], s[24:25], 0, v[44:45]
	v_lshl_add_u64 v[40:41], v[40:41], 0, v[64:65]
	s_waitcnt vmcnt(3)
	v_mov_b32_e32 v40, v244
	v_mov_b32_e32 v41, v245
	v_mov_b32_e32 v42, v246
	v_mov_b32_e32 v43, v247
	v_mov_b32_e32 v47, v42
	v_mov_b32_e32 v49, v43
	s_nop 0
	v_permlane16_swap_b32_e32 v40, v47
	v_permlane16_swap_b32_e32 v41, v49
	v_lshlrev_b32_e32 v42, 16, v40
	v_and_b32_e32 v43, 0xffff0000, v40
	v_lshlrev_b32_e32 v46, 16, v47
	v_and_b32_e32 v47, 0xffff0000, v47
	v_lshlrev_b32_e32 v40, 16, v41
	v_and_b32_e32 v41, 0xffff0000, v41
	v_lshlrev_b32_e32 v48, 16, v49
	v_and_b32_e32 v49, 0xffff0000, v49
	v_pk_fma_f32 v[36:37], v[36:37], 0.5, v[42:43] op_sel_hi:[1,0,1]
	v_pk_fma_f32 v[32:33], v[32:33], 0.5, v[46:47] op_sel_hi:[1,0,1]
	v_pk_fma_f32 v[38:39], v[38:39], 0.5, v[40:41] op_sel_hi:[1,0,1]
	v_pk_fma_f32 v[40:41], v[34:35], 0.5, v[48:49] op_sel_hi:[1,0,1]
	v_cvt_pk_bf16_f32 v34, v36, v37
	v_pk_mul_f32 v[36:37], v[36:37], v[36:37]
	v_pk_mul_f32 v[42:43], v[32:33], v[32:33]
	v_cvt_pk_bf16_f32 v35, v38, v39
	v_pk_mul_f32 v[38:39], v[38:39], v[38:39]
	v_pk_mul_f32 v[46:47], v[40:41], v[40:41]
	v_add_f32_e32 v42, v43, v42
	v_add_f32_e32 v36, v37, v36
	v_add_f32_e32 v37, v46, v42
	v_add_f32_e32 v36, v38, v36
	v_add_f32_e32 v37, v47, v37
	v_add_f32_e32 v36, v39, v36
	v_add_f32_e32 v38, v36, v37
	ds_bpermute_b32 v39, v132, v38
	v_cvt_pk_bf16_f32 v36, v32, v33
	v_cvt_pk_bf16_f32 v37, v40, v41
	s_nop 0
	v_permlane16_swap_b32_e32 v34, v36
	s_waitcnt lgkmcnt(0)
	v_add_f32_e32 v32, v38, v39
	ds_bpermute_b32 v33, v131, v32
	v_lshl_add_u64 v[38:39], s[0:1], 0, v[44:45]
	v_permlane16_swap_b32_e32 v35, v37
	v_lshl_add_u64 v[38:39], v[38:39], 0, v[64:65]
	global_store_dwordx4 v[38:39], v[34:37], off
	s_and_saveexec_b64 s[66:67], s[6:7]
	s_cbranch_execz .LBB0_740
	s_waitcnt lgkmcnt(0)
	v_add_f32_e32 v32, v32, v33
	ds_write_b32 v56, v32 offset:192
; #define SCHED() __builtin_amdgcn_sched_barrier(0)
; template <int EPI, int MB, int NB> ...
;     ...
;   } else if constexpr (EPI == EPI_RES) {
;     const float* res = brow < e.res_split ? e.res0 + (size_t)brow * DM : e.res1 + (size_t)(brow - e.res_split) * DM;
;     const bool rb = e.resb != nullptr;
; #pragma unroll
;     for (int m = 0; m < MB; ++m) {
;       const int lr = lrow0 + m * 16;
;       float sq = 0.f;
;       u32x2 ob[2], rw[2];
;       if (rb) unwiden16(*(const i32x4*)(e.resb + (size_t)(brow + lr) * DM + colw), rw[0], rw[1]);
; #pragma unroll
;       for (int n = 0; n < NB; ++n) {
;         const int col = col0 + n * 16;
;         float4 r4;
;         if (rb) {
;           const u32x2 rr = rw[n];
;           r4.x = __uint_as_float(rr[0] << 16); r4.y = __uint_as_float(rr[0] & 0xffff0000u);
;           r4.z = __uint_as_float(rr[1] << 16); r4.w = __uint_as_float(rr[1] & 0xffff0000u);
;         } else {
;           r4 = *(const float4*)(res + (size_t)lr * DM + col);
;         }
;         float4 v;
;         v.x = r4.x + e.alpha * acc[m][n][0]; v.y = r4.y + e.alpha * acc[m][n][1];
;         v.z = r4.z + e.alpha * acc[m][n][2]; v.w = r4.w + e.alpha * acc[m][n][3];
;         ob[n][0] = pk_bf16(v.x, v.y); ob[n][1] = pk_bf16(v.z, v.w);
;         sq += v.x * v.x + v.y * v.y + v.z * v.z + v.w * v.w;
;       }
;       *(i32x4*)(e.o16 + (size_t)(brow + lr) * DM + colw) = widen16(ob[0], ob[1]);
;       sq += __shfl_xor(sq, 16); sq += __shfl_xor(sq, 32);
;       if (fq == 0) s_part[part_slot * 256 + lr] = sq;
;       SCHED();
;     }
.LBB0_740:
	s_or_b64 exec, exec, s[66:67]
	v_mov_b32_e32 v46, v213
	v_mov_b32_e32 v32, v212
	s_nop 0
	v_add_u32_e32 v34, s11, v46
	v_add_u32_e32 v32, v32, v133
	v_ashrrev_i32_e32 v35, 31, v34
	s_waitcnt lgkmcnt(0)
	v_ashrrev_i32_e32 v33, 31, v32
	v_lshlrev_b64 v[40:41], 12, v[34:35]
	v_lshl_add_u64 v[36:37], s[24:25], 0, v[40:41]
	v_lshlrev_b64 v[32:33], 1, v[32:33]
	v_lshl_add_u64 v[36:37], v[36:37], 0, v[32:33]
	v_mov_b32_e32 v252, 0x10000
	v_mov_b32_e32 v253, 0
	global_load_dwordx4 v[232:235], v[36:37], off
	v_lshl_add_u64 v[248:249], v[36:37], 0, v[252:253]
	global_load_dwordx4 v[236:239], v[248:249], off
	v_lshl_add_u64 v[248:249], v[248:249], 0, v[252:253]
	global_load_dwordx4 v[240:243], v[248:249], off
	v_lshl_add_u64 v[248:249], v[248:249], 0, v[252:253]
	global_load_dwordx4 v[244:247], v[248:249], off
	s_waitcnt vmcnt(3)
	v_mov_b32_e32 v36, v232
	v_mov_b32_e32 v37, v233
	v_mov_b32_e32 v38, v234
	v_mov_b32_e32 v39, v235
	v_mov_b32_e32 v35, v38
	v_mov_b32_e32 v45, v39
	s_nop 0
	v_permlane16_swap_b32_e32 v36, v35
	v_permlane16_swap_b32_e32 v37, v45
	v_lshlrev_b32_e32 v38, 16, v36
	v_and_b32_e32 v39, 0xffff0000, v36
	v_lshlrev_b32_e32 v36, 16, v37
	v_and_b32_e32 v37, 0xffff0000, v37
	v_lshlrev_b32_e32 v42, 16, v35
	v_and_b32_e32 v43, 0xffff0000, v35
	v_lshlrev_b32_e32 v44, 16, v45
	v_and_b32_e32 v45, 0xffff0000, v45
	v_pk_fma_f32 v[38:39], v[28:29], 0.5, v[38:39] op_sel_hi:[1,0,1]
	v_pk_fma_f32 v[30:31], v[30:31], 0.5, v[36:37] op_sel_hi:[1,0,1]
	v_pk_fma_f32 v[24:25], v[24:25], 0.5, v[42:43] op_sel_hi:[1,0,1]
	v_pk_fma_f32 v[26:27], v[26:27], 0.5, v[44:45] op_sel_hi:[1,0,1]
	v_cvt_pk_bf16_f32 v28, v38, v39
	v_cvt_pk_bf16_f32 v29, v30, v31
	v_pk_mul_f32 v[36:37], v[38:39], v[38:39]
	v_pk_mul_f32 v[38:39], v[30:31], v[30:31]
	v_cvt_pk_bf16_f32 v30, v24, v25
	v_pk_mul_f32 v[24:25], v[24:25], v[24:25]
	v_cvt_pk_bf16_f32 v31, v26, v27
	v_pk_mul_f32 v[26:27], v[26:27], v[26:27]
	v_add_f32_e32 v24, v25, v24
	v_add_f32_e32 v25, v37, v36
	v_add_f32_e32 v24, v26, v24
	v_add_f32_e32 v25, v38, v25
	v_add_f32_e32 v24, v27, v24
	v_add_f32_e32 v25, v39, v25
	v_add_f32_e32 v24, v25, v24
	ds_bpermute_b32 v25, v132, v24
	v_lshl_add_u64 v[36:37], s[0:1], 0, v[40:41]
	v_permlane16_swap_b32_e32 v28, v30
	v_permlane16_swap_b32_e32 v29, v31
	s_waitcnt lgkmcnt(0)
	v_add_f32_e32 v25, v24, v25
	ds_bpermute_b32 v26, v131, v25
	v_lshl_add_u64 v[36:37], v[36:37], 0, v[32:33]
	v_lshl_add_u32 v24, v46, 2, s72
	global_store_dwordx4 v[36:37], v[28:31], off
	s_and_saveexec_b64 s[66:67], s[6:7]
	s_cbranch_execz .LBB0_742
	s_waitcnt lgkmcnt(0)
	v_add_f32_e32 v25, v25, v26
	ds_write_b32 v24, v25 offset:4096
.LBB0_742:
	s_or_b64 exec, exec, s[66:67]
	s_waitcnt lgkmcnt(0)
	v_add_u32_e32 v26, 16, v34
	v_ashrrev_i32_e32 v27, 31, v26
	v_lshlrev_b64 v[30:31], 12, v[26:27]
	v_lshl_add_u64 v[26:27], s[24:25], 0, v[30:31]
	v_lshl_add_u64 v[26:27], v[26:27], 0, v[32:33]
	s_waitcnt vmcnt(3)
	v_mov_b32_e32 v26, v236
	v_mov_b32_e32 v27, v237
	v_mov_b32_e32 v28, v238
	v_mov_b32_e32 v29, v239
	v_mov_b32_e32 v25, v28
	v_mov_b32_e32 v35, v29
	s_nop 0
	v_permlane16_swap_b32_e32 v26, v25
	v_permlane16_swap_b32_e32 v27, v35
	v_lshlrev_b32_e32 v28, 16, v26
	v_and_b32_e32 v29, 0xffff0000, v26
	v_lshlrev_b32_e32 v36, 16, v25
	v_and_b32_e32 v37, 0xffff0000, v25
	v_lshlrev_b32_e32 v26, 16, v27
	v_and_b32_e32 v27, 0xffff0000, v27
	v_lshlrev_b32_e32 v38, 16, v35
	v_and_b32_e32 v39, 0xffff0000, v35
	v_pk_fma_f32 v[20:21], v[20:21], 0.5, v[28:29] op_sel_hi:[1,0,1]
	v_pk_fma_f32 v[16:17], v[16:17], 0.5, v[36:37] op_sel_hi:[1,0,1]
	v_pk_fma_f32 v[22:23], v[22:23], 0.5, v[26:27] op_sel_hi:[1,0,1]
	v_pk_fma_f32 v[26:27], v[18:19], 0.5, v[38:39] op_sel_hi:[1,0,1]
	v_cvt_pk_bf16_f32 v18, v20, v21
	v_pk_mul_f32 v[20:21], v[20:21], v[20:21]
	v_pk_mul_f32 v[28:29], v[16:17], v[16:17]
	v_cvt_pk_bf16_f32 v19, v22, v23
	v_pk_mul_f32 v[22:23], v[22:23], v[22:23]
	v_pk_mul_f32 v[36:37], v[26:27], v[26:27]
	v_add_f32_e32 v25, v29, v28
	v_add_f32_e32 v20, v21, v20
	v_add_f32_e32 v21, v36, v25
	v_add_f32_e32 v20, v22, v20
	v_add_f32_e32 v21, v37, v21
	v_add_f32_e32 v20, v23, v20
	v_add_f32_e32 v22, v20, v21
	ds_bpermute_b32 v23, v132, v22
	v_cvt_pk_bf16_f32 v20, v16, v17
	v_cvt_pk_bf16_f32 v21, v26, v27
	s_nop 0
	v_permlane16_swap_b32_e32 v18, v20
	s_waitcnt lgkmcnt(0)
	v_add_f32_e32 v16, v22, v23
	ds_bpermute_b32 v17, v131, v16
	v_lshl_add_u64 v[22:23], s[0:1], 0, v[30:31]
	v_permlane16_swap_b32_e32 v19, v21
	v_lshl_add_u64 v[22:23], v[22:23], 0, v[32:33]
	global_store_dwordx4 v[22:23], v[18:21], off
	s_and_saveexec_b64 s[66:67], s[6:7]
	s_cbranch_execz .LBB0_744
	s_waitcnt lgkmcnt(0)
	v_add_f32_e32 v16, v16, v17
	ds_write_b32 v24, v16 offset:4160
; #define SCHED() __builtin_amdgcn_sched_barrier(0)
; template <int EPI, int MB, int NB> ...
;     ...
;   } else if constexpr (EPI == EPI_RES) {
;     const float* res = brow < e.res_split ? e.res0 + (size_t)brow * DM : e.res1 + (size_t)(brow - e.res_split) * DM;
;     const bool rb = e.resb != nullptr;
; #pragma unroll
;     for (int m = 0; m < MB; ++m) {
;       const int lr = lrow0 + m * 16;
;       float sq = 0.f;
;       u32x2 ob[2], rw[2];
;       if (rb) unwiden16(*(const i32x4*)(e.resb + (size_t)(brow + lr) * DM + colw), rw[0], rw[1]);
; #pragma unroll
;       for (int n = 0; n < NB; ++n) {
;         const int col = col0 + n * 16;
;         float4 r4;
;         if (rb) {
;           const u32x2 rr = rw[n];
;           r4.x = __uint_as_float(rr[0] << 16); r4.y = __uint_as_float(rr[0] & 0xffff0000u);
;           r4.z = __uint_as_float(rr[1] << 16); r4.w = __uint_as_float(rr[1] & 0xffff0000u);
;         } else {
;           r4 = *(const float4*)(res + (size_t)lr * DM + col);
;         }
;         float4 v;
;         v.x = r4.x + e.alpha * acc[m][n][0]; v.y = r4.y + e.alpha * acc[m][n][1];
;         v.z = r4.z + e.alpha * acc[m][n][2]; v.w = r4.w + e.alpha * acc[m][n][3];
;         ob[n][0] = pk_bf16(v.x, v.y); ob[n][1] = pk_bf16(v.z, v.w);
;         sq += v.x * v.x + v.y * v.y + v.z * v.z + v.w * v.w;
;       }
;       *(i32x4*)(e.o16 + (size_t)(brow + lr) * DM + colw) = widen16(ob[0], ob[1]);
;       sq += __shfl_xor(sq, 16); sq += __shfl_xor(sq, 32);
;       if (fq == 0) s_part[part_slot * 256 + lr] = sq;
;       SCHED();
;     }
.LBB0_744:
	s_or_b64 exec, exec, s[66:67]
	v_add_u32_e32 v16, 32, v34
	s_waitcnt lgkmcnt(0)
	v_ashrrev_i32_e32 v17, 31, v16
	v_lshlrev_b64 v[20:21], 12, v[16:17]
	v_lshl_add_u64 v[16:17], s[24:25], 0, v[20:21]
	v_lshl_add_u64 v[16:17], v[16:17], 0, v[32:33]
	s_waitcnt vmcnt(3)
	v_mov_b32_e32 v16, v240
	v_mov_b32_e32 v17, v241
	v_mov_b32_e32 v18, v242
	v_mov_b32_e32 v19, v243
	v_mov_b32_e32 v23, v18
	v_mov_b32_e32 v25, v19
	s_nop 0
	v_permlane16_swap_b32_e32 v16, v23
	v_permlane16_swap_b32_e32 v17, v25
	v_lshlrev_b32_e32 v18, 16, v16
	v_and_b32_e32 v19, 0xffff0000, v16
	v_lshlrev_b32_e32 v22, 16, v23
	v_and_b32_e32 v23, 0xffff0000, v23
	v_lshlrev_b32_e32 v16, 16, v17
	v_and_b32_e32 v17, 0xffff0000, v17
	v_lshlrev_b32_e32 v26, 16, v25
	v_and_b32_e32 v27, 0xffff0000, v25
	v_pk_fma_f32 v[12:13], v[12:13], 0.5, v[18:19] op_sel_hi:[1,0,1]
	v_pk_fma_f32 v[8:9], v[8:9], 0.5, v[22:23] op_sel_hi:[1,0,1]
	v_pk_fma_f32 v[14:15], v[14:15], 0.5, v[16:17] op_sel_hi:[1,0,1]
	v_pk_fma_f32 v[16:17], v[10:11], 0.5, v[26:27] op_sel_hi:[1,0,1]
	v_cvt_pk_bf16_f32 v10, v12, v13
	v_pk_mul_f32 v[12:13], v[12:13], v[12:13]
	v_pk_mul_f32 v[18:19], v[8:9], v[8:9]
	v_cvt_pk_bf16_f32 v11, v14, v15
	v_pk_mul_f32 v[14:15], v[14:15], v[14:15]
	v_pk_mul_f32 v[22:23], v[16:17], v[16:17]
	v_add_f32_e32 v18, v19, v18
	v_add_f32_e32 v12, v13, v12
	v_add_f32_e32 v13, v22, v18
	v_add_f32_e32 v12, v14, v12
	v_add_f32_e32 v13, v23, v13
	v_add_f32_e32 v12, v15, v12
	v_add_f32_e32 v14, v12, v13
	ds_bpermute_b32 v15, v132, v14
	v_cvt_pk_bf16_f32 v12, v8, v9
	v_cvt_pk_bf16_f32 v13, v16, v17
	s_nop 0
	v_permlane16_swap_b32_e32 v10, v12
	s_waitcnt lgkmcnt(0)
	v_add_f32_e32 v8, v14, v15
	ds_bpermute_b32 v9, v131, v8
	v_lshl_add_u64 v[14:15], s[0:1], 0, v[20:21]
	v_permlane16_swap_b32_e32 v11, v13
	v_lshl_add_u64 v[14:15], v[14:15], 0, v[32:33]
	global_store_dwordx4 v[14:15], v[10:13], off
	s_and_saveexec_b64 s[66:67], s[6:7]
	s_cbranch_execz .LBB0_746
	s_waitcnt lgkmcnt(0)
	v_add_f32_e32 v8, v8, v9
	ds_write_b32 v24, v8 offset:4224
.LBB0_746:
	s_or_b64 exec, exec, s[66:67]
	v_add_u32_e32 v8, 48, v34
	s_waitcnt lgkmcnt(0)
	v_ashrrev_i32_e32 v9, 31, v8
	v_lshlrev_b64 v[12:13], 12, v[8:9]
	v_lshl_add_u64 v[8:9], s[24:25], 0, v[12:13]
	v_lshl_add_u64 v[8:9], v[8:9], 0, v[32:33]
	s_waitcnt vmcnt(3)
	v_mov_b32_e32 v8, v244
	v_mov_b32_e32 v9, v245
	v_mov_b32_e32 v10, v246
	v_mov_b32_e32 v11, v247
	v_mov_b32_e32 v15, v10
	v_mov_b32_e32 v17, v11
	s_nop 0
	v_permlane16_swap_b32_e32 v8, v15
	v_permlane16_swap_b32_e32 v9, v17
	v_lshlrev_b32_e32 v10, 16, v8
	v_and_b32_e32 v11, 0xffff0000, v8
	v_lshlrev_b32_e32 v14, 16, v15
	v_and_b32_e32 v15, 0xffff0000, v15
	v_lshlrev_b32_e32 v8, 16, v9
	v_and_b32_e32 v9, 0xffff0000, v9
	v_lshlrev_b32_e32 v16, 16, v17
	v_and_b32_e32 v17, 0xffff0000, v17
	v_pk_fma_f32 v[4:5], v[4:5], 0.5, v[10:11] op_sel_hi:[1,0,1]
	v_pk_fma_f32 v[0:1], v[0:1], 0.5, v[14:15] op_sel_hi:[1,0,1]
	v_pk_fma_f32 v[6:7], v[6:7], 0.5, v[8:9] op_sel_hi:[1,0,1]
	v_pk_fma_f32 v[8:9], v[2:3], 0.5, v[16:17] op_sel_hi:[1,0,1]
	v_cvt_pk_bf16_f32 v2, v4, v5
	v_pk_mul_f32 v[4:5], v[4:5], v[4:5]
	v_pk_mul_f32 v[10:11], v[0:1], v[0:1]
	v_cvt_pk_bf16_f32 v3, v6, v7
	v_pk_mul_f32 v[6:7], v[6:7], v[6:7]
	v_pk_mul_f32 v[14:15], v[8:9], v[8:9]
	v_add_f32_e32 v10, v11, v10
	v_add_f32_e32 v4, v5, v4
	v_add_f32_e32 v5, v14, v10
	v_add_f32_e32 v4, v6, v4
	v_add_f32_e32 v5, v15, v5
	v_add_f32_e32 v4, v7, v4
	v_add_f32_e32 v6, v4, v5
	ds_bpermute_b32 v7, v132, v6
	v_cvt_pk_bf16_f32 v4, v0, v1
	v_cvt_pk_bf16_f32 v5, v8, v9
	s_nop 0
	v_permlane16_swap_b32_e32 v2, v4
	s_waitcnt lgkmcnt(0)
	v_add_f32_e32 v0, v6, v7
	ds_bpermute_b32 v1, v131, v0
	v_lshl_add_u64 v[6:7], s[0:1], 0, v[12:13]
	v_permlane16_swap_b32_e32 v3, v5
	v_lshl_add_u64 v[6:7], v[6:7], 0, v[32:33]
	global_store_dwordx4 v[6:7], v[2:5], off
	s_and_saveexec_b64 s[66:67], s[6:7]
	s_cbranch_execz .LBB0_748
	s_waitcnt lgkmcnt(0)
	v_add_f32_e32 v0, v0, v1
	ds_write_b32 v24, v0 offset:4288
